# attention and scan co-scheduled: workgroups with blockIdx/8 < 16 run all attention units, the other 128 run the scan (64 rows each, 8 compute waves)
# speedup vs baseline: 1.0352x; 1.0122x over previous
; __device__ __forceinline__ int bid_() { int b = blockIdx.x; asm volatile("" : "+s"(b)); return b; }
; __device__ __forceinline__ void phase_scan(CParams& P, LAS unsigned char* lds) {
;     ...
;     const int bx_ = bid_(); const int vcu_ = (nb_ % 8 == 0) ? (bx_ % 8) * (nb_ / 8) + bx_ / 8 : bx_;
;     for (int task = vcu_; task < GSEQ * 8 * 2 * 2; task += nb_) {
;         const int rowhalf = task & 1, dir = (task >> 1) & 1, h = (task >> 2) & 7, s = task >> 5;
;         float* OUT = (float*)(P.ws + WS_P2) + (size_t)dir * TG * 512;
;         __syncthreads();
;         if (wid >= 4) {
;             const int ltid = tid - 256; f16x8 v[6];
;     ...
;             SC_GLOAD(0); SC_WRITE(0); SC_GLOAD(1);
; #pragma unroll 1
;             for (int c = 0; c < NCH; ++c) {
;                 __syncthreads();
;                 if (c + 1 < NCH) { SC_WRITE(c + 1); if (c + 2 < NCH) SC_GLOAD(c + 2); }
;             }
;             __syncthreads();
;     ...
;         } else {
;             const int rl = lane >> 3, oct = lane & 7, rloc = wid * 8 + rl;
;             __builtin_amdgcn_s_setprio(3);
;             f32x4 s0 = {0.f, 0.f, 0.f, 0.f}, s1 = {0.f, 0.f, 0.f, 0.f};
;             float* op = OUT + ((size_t)s * SEQ + (dir ? SEQ - 1 : 0)) * 512 + h * 64 + rowhalf * 32 + rloc; const long ostep = dir ? -512 : 512;
.LBB0_235:
	s_andn2_b64 vcc, exec, s[4:5]
	s_cbranch_vccnz .LBB0_627
	s_cmp_gt_i32 s14, 8
	s_mov_b64 s[4:5], -1
	s_cbranch_scc0 .LBB0_606
	s_branch .LBB0_605
.Lr3_scan:
	s_waitcnt vmcnt(0)
	s_lshr_b32 s4, s2, 3
	s_add_i32 s4, s4, -16
	s_and_b32 s7, s2, 7
	s_and_b32 s5, s4, 1
	s_bfe_u32 s6, s4, 0x30001
	s_mul_i32 s9, s7, 0xc00000
	s_mul_i32 s12, s6, 0x180
	s_add_i32 s9, s9, s12
	s_add_i32 s12, s9, 0x1a000000
	s_add_u32 s40, s22, s12
	s_addc_u32 s41, s23, 0
	s_mul_i32 s12, s5, 0x6000000
	s_add_i32 s12, s12, s9
	s_add_i32 s12, s12, 0x20000000
	s_add_u32 s42, s22, s12
	s_addc_u32 s43, s23, 0
	s_lshl_b32 s12, s7, 22
	s_lshl_b32 s15, s6, 7
	s_add_i32 s12, s12, s15
	s_add_i32 s12, s12, 0x2e000000
	s_add_u32 s44, s22, s12
	s_addc_u32 s45, s23, 0
	s_lshl_b32 s12, s7, 23
	s_lshl_b32 s15, s6, 8
	s_add_i32 s12, s12, s15
	s_lshl_b32 s15, s5, 26
	s_add_i32 s12, s12, s15
	s_add_i32 s12, s12, 0x8000000
	s_add_u32 s10, s22, s12
	s_addc_u32 s11, s23, 0
	s_cmp_eq_u32 s5, 0
	s_cselect_b32 s46, 0, 0xfff
	s_mov_b32 s47, 0xfffe8000
	s_cselect_b32 s48, 0x18000, s47
	s_cselect_b32 s49, 0, -1
	s_mov_b32 s47, 0xffff8000
	s_cselect_b32 s36, 0x8000, s47
	s_cselect_b32 s37, 0, -1
	s_mov_b32 s47, 0xffffe000
	s_cselect_b32 s13, 0x2000, s47
	s_mov_b32 s50, 0xaaaaaaaa
	s_mov_b32 s51, 0xaaaaaaaa
	s_mov_b32 s52, 0xcccccccc
	s_mov_b32 s53, 0xcccccccc
	v_lshrrev_b32_e32 v0, 6, v222
	v_and_b32_e32 v6, 15, v222
	v_readfirstlane_b32 s28, v0
	v_lshrrev_b32_e32 v7, 4, v222
	s_cmp_lt_u32 s28, 4
	s_cselect_b32 s36, s48, s36
	s_cselect_b32 s37, s49, s37
	v_xor_b32_e32 v1, s46, v7
	v_mul_u32_u24_e32 v1, 0xc00, v1
	v_lshlrev_b32_e32 v64, 4, v6
	v_add_u32_e32 v130, v1, v64
	v_mov_b32_e32 v131, 0
	v_and_b32_e32 v1, 8, v6
	v_lshlrev_b32_e32 v1, 4, v1
	v_add_u32_e32 v128, v130, v1
	v_mov_b32_e32 v129, 0
	v_lshl_add_u64 v[152:153], s[40:41], 0, v[128:129]
	v_lshl_add_u64 v[154:155], s[42:43], 0, v[130:131]
	v_mul_u32_u24_e32 v0, 0x500, v7
	v_and_b32_e32 v1, 7, v6
	v_lshlrev_b32_e32 v1, 5, v1
	v_add_u32_e32 v0, v0, v1
	v_and_b32_e32 v1, 8, v6
	v_lshlrev_b32_e32 v127, 7, v1
	v_sub_u32_e32 v127, 0x400, v127
	v_add_u32_e32 v178, v0, v127
	v_lshlrev_b32_e32 v127, 5, v1
	v_add_u32_e32 v127, 0x100, v127
	v_add_u32_e32 v179, v0, v127
	v_lshrrev_b32_e32 v0, 3, v222
	v_and_b32_e32 v0, 31, v0
	v_and_b32_e32 v1, 7, v222
	v_xor_b32_e32 v127, s46, v0
	s_cmp_lt_u32 s28, 4
	s_cbranch_scc0 .Lr3_roleV
	v_mul_u32_u24_e32 v127, 0xc00, v127
	v_lshlrev_b32_e32 v128, 4, v1
	v_add_u32_e32 v128, v127, v128
	v_add_u32_e32 v128, 0x100, v128
	v_mov_b32_e32 v129, 0
	v_lshl_add_u64 v[156:157], s[42:43], 0, v[128:129]
	v_mul_u32_u24_e32 v0, 0x500, v0
	v_lshlrev_b32_e32 v1, 5, v1
	v_add_u32_e32 v0, v0, v1
	v_add_u32_e32 v180, 0x300, v0
	s_branch .Lr3_roleDone
.Lr3_roleV:
	v_lshlrev_b32_e32 v127, 10, v127
	v_lshlrev_b32_e32 v128, 4, v1
	v_add_u32_e32 v128, v127, v128
	v_mov_b32_e32 v129, 0
	v_lshl_add_u64 v[156:157], s[44:45], 0, v[128:129]
	v_lshlrev_b32_e32 v0, 3, v0
	v_lshlrev_b32_e32 v1, 10, v1
	v_add_u32_e32 v0, v0, v1
	v_add_u32_e32 v180, 0xa000, v0
; #define LAS __attribute__((address_space(3)))
; __device__ __forceinline__ void phase_scan(CParams& P, LAS unsigned char* lds) {
;     ...
;             SC_GLOAD(0); SC_WRITE(0); SC_GLOAD(1);
; #pragma unroll 1
;             for (int c = 0; c < NCH; ++c) {
;                 __syncthreads();
;                 if (c + 1 < NCH) { SC_WRITE(c + 1); if (c + 2 < NCH) SC_GLOAD(c + 2); }
;             }
;             __syncthreads();
;     ...
;         } else {
;             const int rl = lane >> 3, oct = lane & 7, rloc = wid * 8 + rl;
;             __builtin_amdgcn_s_setprio(3);
;             f32x4 s0 = {0.f, 0.f, 0.f, 0.f}, s1 = {0.f, 0.f, 0.f, 0.f};
;             float* op = OUT + ((size_t)s * SEQ + (dir ? SEQ - 1 : 0)) * 512 + h * 64 + rowhalf * 32 + rloc; const long ostep = dir ? -512 : 512;
;     ...
;             f32x4 Ar0, Ar1, Aw0, Aw1, Ak0, Ak1, Aq0, Aq1, Ab0, Ab1, Br0, Br1, Bw0, Bw1, Bk0, Bk1, Bq0, Bq1, Bb0, Bb1; float Avv, Bvv;
; #pragma unroll 1
;             for (int c = 0; c < NCH; ++c) {
;                 __syncthreads();
;                 const LAS float* base = lf + (c & 1) * BUFF + 8 * oct;
;                 SC_LOAD(A, base);
.Lr3_roleDone:
	v_lshlrev_b32_e32 v98, 4, v6
	v_lshlrev_b32_e32 v0, 8, v7
	v_add_u32_e32 v99, 0xa000, v0
	v_and_b32_e32 v0, 3, v6
	v_xor_b32_e32 v0, s46, v0
	v_lshlrev_b32_e32 v0, 11, v0
	v_lshl_add_u32 v102, v7, 3, v0
	v_mov_b32_e32 v2, 0
	v_mov_b32_e32 v3, 0
	v_mov_b32_e32 v4, 0
	v_mov_b32_e32 v5, 0
	v_mov_b32_e32 v6, 0
	v_mov_b32_e32 v7, 0
	v_mov_b32_e32 v8, 0
	v_mov_b32_e32 v9, 0
	global_load_dwordx4 v[158:161], v[152:153], off
	global_load_dwordx4 v[162:165], v[154:155], off
	global_load_dwordx4 v[166:169], v[156:157], off
	v_lshl_add_u64 v[152:153], v[152:153], 0, s[48:49]
	v_lshl_add_u64 v[154:155], v[154:155], 0, s[48:49]
	v_lshl_add_u64 v[156:157], v[156:157], 0, s[36:37]
	s_mov_b32 s14, 0
	s_waitcnt vmcnt(0)
	v_add_u32_e32 v181, s14, v178
	v_cvt_f32_f16_e32 v170, v158
	v_cvt_f32_f16_sdwa v171, v158 dst_sel:DWORD dst_unused:UNUSED_PAD src0_sel:WORD_1
	v_cvt_f32_f16_e32 v172, v159
	v_cvt_f32_f16_sdwa v173, v159 dst_sel:DWORD dst_unused:UNUSED_PAD src0_sel:WORD_1
	v_cvt_f32_f16_e32 v174, v160
	v_cvt_f32_f16_sdwa v175, v160 dst_sel:DWORD dst_unused:UNUSED_PAD src0_sel:WORD_1
	v_cvt_f32_f16_e32 v176, v161
	v_cvt_f32_f16_sdwa v177, v161 dst_sel:DWORD dst_unused:UNUSED_PAD src0_sel:WORD_1
	ds_write_b128 v181, v[170:173]
	ds_write_b128 v181, v[174:177] offset:16
	v_add_u32_e32 v181, s14, v179
	v_cvt_f32_f16_e32 v170, v162
	v_cvt_f32_f16_sdwa v171, v162 dst_sel:DWORD dst_unused:UNUSED_PAD src0_sel:WORD_1
	v_cvt_f32_f16_e32 v172, v163
	v_cvt_f32_f16_sdwa v173, v163 dst_sel:DWORD dst_unused:UNUSED_PAD src0_sel:WORD_1
	v_cvt_f32_f16_e32 v174, v164
	v_cvt_f32_f16_sdwa v175, v164 dst_sel:DWORD dst_unused:UNUSED_PAD src0_sel:WORD_1
	v_cvt_f32_f16_e32 v176, v165
	v_cvt_f32_f16_sdwa v177, v165 dst_sel:DWORD dst_unused:UNUSED_PAD src0_sel:WORD_1
	ds_write_b128 v181, v[170:173]
	ds_write_b128 v181, v[174:177] offset:16
	v_add_u32_e32 v181, s14, v180
	v_cvt_f32_f16_e32 v170, v166
	v_cvt_f32_f16_sdwa v171, v166 dst_sel:DWORD dst_unused:UNUSED_PAD src0_sel:WORD_1
	v_cvt_f32_f16_e32 v172, v167
	v_cvt_f32_f16_sdwa v173, v167 dst_sel:DWORD dst_unused:UNUSED_PAD src0_sel:WORD_1
	v_cvt_f32_f16_e32 v174, v168
	v_cvt_f32_f16_sdwa v175, v168 dst_sel:DWORD dst_unused:UNUSED_PAD src0_sel:WORD_1
	v_cvt_f32_f16_e32 v176, v169
	v_cvt_f32_f16_sdwa v177, v169 dst_sel:DWORD dst_unused:UNUSED_PAD src0_sel:WORD_1
	s_cmp_lt_u32 s28, 4
	s_cbranch_scc0 .Lr3_cwV1
	ds_write_b128 v181, v[170:173]
	ds_write_b128 v181, v[174:177] offset:16
	s_branch .Lr3_cwdone1
.Lr3_cwV1:
	ds_write_b64 v181, v[170:171] offset:0
	ds_write_b64 v181, v[172:173] offset:256
	ds_write_b64 v181, v[174:175] offset:512
	ds_write_b64 v181, v[176:177] offset:768
.Lr3_cwdone1:
	global_load_dwordx4 v[158:161], v[152:153], off
	global_load_dwordx4 v[162:165], v[154:155], off
	global_load_dwordx4 v[166:169], v[156:157], off
	v_lshl_add_u64 v[152:153], v[152:153], 0, s[48:49]
	v_lshl_add_u64 v[154:155], v[154:155], 0, s[48:49]
	v_lshl_add_u64 v[156:157], v[156:157], 0, s[36:37]
	s_mov_b32 s12, 0
.Lr3_chunk:
	s_waitcnt lgkmcnt(0)
	s_barrier
	v_add_u32_e32 v100, s14, v98
	v_add_u32_e32 v101, s14, v99
	ds_read_b128 v[70:73], v101 offset:0
	ds_read_b128 v[10:13], v100 offset:0
	ds_read_b128 v[18:21], v100 offset:512
	ds_read_b128 v[14:17], v100 offset:256
	ds_read_b128 v[22:25], v100 offset:768
	ds_read_b128 v[26:29], v100 offset:1024
	ds_read_b128 v[30:33], v100 offset:1280
	ds_read_b128 v[38:41], v100 offset:1792
	ds_read_b128 v[34:37], v100 offset:1536
	ds_read_b128 v[42:45], v100 offset:2048
	ds_read_b128 v[46:49], v100 offset:2304
	s_cmp_ge_u32 s12, 0x7f
	s_cbranch_scc1 .Lr3_noload
	s_cmp_eq_u32 s12, 0
	s_cbranch_scc0 .Lr3_w8
	s_waitcnt vmcnt(0)
.Lr3_w8:
	s_waitcnt vmcnt(8)
	s_sub_i32 s15, 0xc000, s14
	v_add_u32_e32 v181, s15, v178
	v_cvt_f32_f16_e32 v170, v158
	v_cvt_f32_f16_sdwa v171, v158 dst_sel:DWORD dst_unused:UNUSED_PAD src0_sel:WORD_1
	v_cvt_f32_f16_e32 v172, v159
	v_cvt_f32_f16_sdwa v173, v159 dst_sel:DWORD dst_unused:UNUSED_PAD src0_sel:WORD_1
	v_cvt_f32_f16_e32 v174, v160
	v_cvt_f32_f16_sdwa v175, v160 dst_sel:DWORD dst_unused:UNUSED_PAD src0_sel:WORD_1
	v_cvt_f32_f16_e32 v176, v161
	v_cvt_f32_f16_sdwa v177, v161 dst_sel:DWORD dst_unused:UNUSED_PAD src0_sel:WORD_1
	ds_write_b128 v181, v[170:173]
	ds_write_b128 v181, v[174:177] offset:16
	v_add_u32_e32 v181, s15, v179
	v_cvt_f32_f16_e32 v170, v162
	v_cvt_f32_f16_sdwa v171, v162 dst_sel:DWORD dst_unused:UNUSED_PAD src0_sel:WORD_1
	v_cvt_f32_f16_e32 v172, v163
	v_cvt_f32_f16_sdwa v173, v163 dst_sel:DWORD dst_unused:UNUSED_PAD src0_sel:WORD_1
	v_cvt_f32_f16_e32 v174, v164
	v_cvt_f32_f16_sdwa v175, v164 dst_sel:DWORD dst_unused:UNUSED_PAD src0_sel:WORD_1
	v_cvt_f32_f16_e32 v176, v165
	v_cvt_f32_f16_sdwa v177, v165 dst_sel:DWORD dst_unused:UNUSED_PAD src0_sel:WORD_1
	ds_write_b128 v181, v[170:173]
	ds_write_b128 v181, v[174:177] offset:16
	v_add_u32_e32 v181, s15, v180
	v_cvt_f32_f16_e32 v170, v166
	v_cvt_f32_f16_sdwa v171, v166 dst_sel:DWORD dst_unused:UNUSED_PAD src0_sel:WORD_1
	v_cvt_f32_f16_e32 v172, v167
	v_cvt_f32_f16_sdwa v173, v167 dst_sel:DWORD dst_unused:UNUSED_PAD src0_sel:WORD_1
	v_cvt_f32_f16_e32 v174, v168
	v_cvt_f32_f16_sdwa v175, v168 dst_sel:DWORD dst_unused:UNUSED_PAD src0_sel:WORD_1
	v_cvt_f32_f16_e32 v176, v169
	v_cvt_f32_f16_sdwa v177, v169 dst_sel:DWORD dst_unused:UNUSED_PAD src0_sel:WORD_1
	s_cmp_lt_u32 s28, 4
	s_cbranch_scc0 .Lr3_cwV2
	ds_write_b128 v181, v[170:173]
	ds_write_b128 v181, v[174:177] offset:16
	s_branch .Lr3_cwdone2

; #define LAS __attribute__((address_space(3)))
; __device__ __forceinline__ void phase_scan(CParams& P, LAS unsigned char* lds) {
;     ...
;             for (int c = 0; c < NCH; ++c) {
;                 __syncthreads();
;                 if (c + 1 < NCH) { SC_WRITE(c + 1); if (c + 2 < NCH) SC_GLOAD(c + 2); }
;             }
;             __syncthreads();
;     ...
;         } else {
;             const int rl = lane >> 3, oct = lane & 7, rloc = wid * 8 + rl;
;             __builtin_amdgcn_s_setprio(3);
;             f32x4 s0 = {0.f, 0.f, 0.f, 0.f}, s1 = {0.f, 0.f, 0.f, 0.f};
;             float* op = OUT + ((size_t)s * SEQ + (dir ? SEQ - 1 : 0)) * 512 + h * 64 + rowhalf * 32 + rloc; const long ostep = dir ? -512 : 512;
;     ...
;             f32x4 Ar0, Ar1, Aw0, Aw1, Ak0, Ak1, Aq0, Aq1, Ab0, Ab1, Br0, Br1, Bw0, Bw1, Bk0, Bk1, Bq0, Bq1, Bb0, Bb1; float Avv, Bvv;
; #pragma unroll 1
;             for (int c = 0; c < NCH; ++c) {
;                 __syncthreads();
;                 const LAS float* base = lf + (c & 1) * BUFF + 8 * oct;
;                 SC_LOAD(A, base);
; #pragma unroll 2
;                 for (int j = 0; j < CH; j += 2) { const LAS float* sp = base + j * STEPF;
;                     SC_LOAD(B, sp + STEPF); SC_STEP(A);
.Lr3_cwdone2:
	s_cmp_ge_u32 s12, 0x7e
	s_cbranch_scc1 .Lr3_noload
	global_load_dwordx4 v[158:161], v[152:153], off
	global_load_dwordx4 v[162:165], v[154:155], off
	global_load_dwordx4 v[166:169], v[156:157], off
	v_lshl_add_u64 v[152:153], v[152:153], 0, s[48:49]
	v_lshl_add_u64 v[154:155], v[154:155], 0, s[48:49]
	v_lshl_add_u64 v[156:157], v[156:157], 0, s[36:37]
.Lr3_noload:
	s_cmp_lt_u32 s28, 4
	s_cbranch_scc1 .Lr3_nostag
	s_sleep 1
.Lr3_nostag:
	s_waitcnt lgkmcnt(0)
	v_pk_mul_f32 v[78:79], v[2:3], v[10:11] op_sel_hi:[1,0]
	v_pk_fma_f32 v[78:79], v[4:5], v[10:11], v[78:79] op_sel:[0,1,0] op_sel_hi:[1,1,1]
	v_pk_fma_f32 v[78:79], v[6:7], v[12:13], v[78:79] op_sel_hi:[1,0,1]
	v_pk_fma_f32 v[78:79], v[8:9], v[12:13], v[78:79] op_sel:[0,1,0] op_sel_hi:[1,1,1]
	v_pk_mul_f32 v[82:83], v[70:71], v[18:19] op_sel_hi:[1,0]
	v_pk_mul_f32 v[84:85], v[70:71], v[18:19] op_sel:[0,1] op_sel_hi:[1,1]
	v_add_f32_dpp v78, v78, v78 quad_perm:[1,0,3,2] row_mask:0xf bank_mask:0xf bound_ctrl:1
	v_add_f32_dpp v79, v79, v79 quad_perm:[1,0,3,2] row_mask:0xf bank_mask:0xf bound_ctrl:1
	v_pk_mul_f32 v[86:87], v[70:71], v[20:21] op_sel_hi:[1,0]
	ds_read_b128 v[132:135], v100 offset:2560
	v_add_f32_dpp v78, v78, v78 quad_perm:[2,3,0,1] row_mask:0xf bank_mask:0xf bound_ctrl:1
	v_add_f32_dpp v79, v79, v79 quad_perm:[2,3,0,1] row_mask:0xf bank_mask:0xf bound_ctrl:1
	v_pk_mul_f32 v[88:89], v[70:71], v[20:21] op_sel:[0,1] op_sel_hi:[1,1]
	ds_read_b128 v[140:143], v100 offset:3072
	v_add_f32_dpp v78, v78, v78 row_half_mirror row_mask:0xf bank_mask:0xf bound_ctrl:1
	v_add_f32_dpp v79, v79, v79 row_half_mirror row_mask:0xf bank_mask:0xf bound_ctrl:1
	v_pk_fma_f32 v[82:83], v[2:3], v[14:15], v[82:83] op_sel_hi:[1,0,1]
	ds_read_b128 v[136:139], v100 offset:2816
	v_add_f32_dpp v78, v78, v78 row_mirror row_mask:0xf bank_mask:0xf bound_ctrl:1
	v_add_f32_dpp v79, v79, v79 row_mirror row_mask:0xf bank_mask:0xf bound_ctrl:1
	v_pk_fma_f32 v[84:85], v[4:5], v[14:15], v[84:85] op_sel:[0,1,0] op_sel_hi:[1,1,1]
	ds_read_b128 v[144:147], v100 offset:3328
	v_pk_fma_f32 v[86:87], v[6:7], v[16:17], v[86:87] op_sel_hi:[1,0,1]
	ds_read_b128 v[148:151], v100 offset:3584
	v_pk_fma_f32 v[88:89], v[8:9], v[16:17], v[88:89] op_sel:[0,1,0] op_sel_hi:[1,1,1]
	ds_read_b128 v[74:77], v101 offset:16
	v_pk_fma_f32 v[2:3], v[78:79], v[22:23], v[82:83] op_sel_hi:[1,0,1]
	v_pk_fma_f32 v[4:5], v[78:79], v[22:23], v[84:85] op_sel:[0,1,0] op_sel_hi:[1,1,1]
	v_pk_fma_f32 v[6:7], v[78:79], v[24:25], v[86:87] op_sel_hi:[1,0,1]
	v_pk_fma_f32 v[8:9], v[78:79], v[24:25], v[88:89] op_sel:[0,1,0] op_sel_hi:[1,1,1]
	s_waitcnt lgkmcnt(6)
	v_pk_mul_f32 v[78:79], v[2:3], v[30:31] op_sel_hi:[1,0]
	v_pk_mul_f32 v[90:91], v[2:3], v[26:27] op_sel_hi:[1,0]
	v_pk_fma_f32 v[78:79], v[4:5], v[30:31], v[78:79] op_sel:[0,1,0] op_sel_hi:[1,1,1]
	v_pk_fma_f32 v[90:91], v[4:5], v[26:27], v[90:91] op_sel:[0,1,0] op_sel_hi:[1,1,1]
	v_pk_fma_f32 v[78:79], v[6:7], v[32:33], v[78:79] op_sel_hi:[1,0,1]
	v_pk_fma_f32 v[90:91], v[6:7], v[28:29], v[90:91] op_sel_hi:[1,0,1]
	v_pk_fma_f32 v[78:79], v[8:9], v[32:33], v[78:79] op_sel:[0,1,0] op_sel_hi:[1,1,1]
	v_pk_mul_f32 v[82:83], v[72:73], v[38:39] op_sel_hi:[1,0]
	v_pk_fma_f32 v[90:91], v[8:9], v[28:29], v[90:91] op_sel:[0,1,0] op_sel_hi:[1,1,1]
	v_pk_mul_f32 v[84:85], v[72:73], v[38:39] op_sel:[0,1] op_sel_hi:[1,1]
	v_add_f32_dpp v78, v78, v78 quad_perm:[1,0,3,2] row_mask:0xf bank_mask:0xf bound_ctrl:1
	v_add_f32_dpp v79, v79, v79 quad_perm:[1,0,3,2] row_mask:0xf bank_mask:0xf bound_ctrl:1
	v_pk_mul_f32 v[86:87], v[72:73], v[40:41] op_sel_hi:[1,0]
	ds_read_b128 v[10:13], v100 offset:3840
	v_add_f32_dpp v78, v78, v78 quad_perm:[2,3,0,1] row_mask:0xf bank_mask:0xf bound_ctrl:1
	v_add_f32_dpp v79, v79, v79 quad_perm:[2,3,0,1] row_mask:0xf bank_mask:0xf bound_ctrl:1
	v_pk_mul_f32 v[88:89], v[72:73], v[40:41] op_sel:[0,1] op_sel_hi:[1,1]
	ds_read_b128 v[18:21], v100 offset:4352
	v_add_f32_dpp v78, v78, v78 row_half_mirror row_mask:0xf bank_mask:0xf bound_ctrl:1
	v_add_f32_dpp v79, v79, v79 row_half_mirror row_mask:0xf bank_mask:0xf bound_ctrl:1
	v_pk_fma_f32 v[82:83], v[2:3], v[34:35], v[82:83] op_sel_hi:[1,0,1]
	ds_read_b128 v[14:17], v100 offset:4096
	v_add_f32_dpp v78, v78, v78 row_mirror row_mask:0xf bank_mask:0xf bound_ctrl:1
	v_add_f32_dpp v79, v79, v79 row_mirror row_mask:0xf bank_mask:0xf bound_ctrl:1
	v_pk_fma_f32 v[84:85], v[4:5], v[34:35], v[84:85] op_sel:[0,1,0] op_sel_hi:[1,1,1]
	ds_read_b128 v[22:25], v100 offset:4608
	v_pk_fma_f32 v[86:87], v[6:7], v[36:37], v[86:87] op_sel_hi:[1,0,1]
	ds_read_b128 v[26:29], v100 offset:4864
	v_pk_fma_f32 v[88:89], v[8:9], v[36:37], v[88:89] op_sel:[0,1,0] op_sel_hi:[1,1,1]
	v_pk_fma_f32 v[2:3], v[78:79], v[42:43], v[82:83] op_sel_hi:[1,0,1]
	v_pk_fma_f32 v[4:5], v[78:79], v[42:43], v[84:85] op_sel:[0,1,0] op_sel_hi:[1,1,1]
	v_pk_fma_f32 v[6:7], v[78:79], v[44:45], v[86:87] op_sel_hi:[1,0,1]
	v_pk_fma_f32 v[8:9], v[78:79], v[44:45], v[88:89] op_sel:[0,1,0] op_sel_hi:[1,1,1]
	s_waitcnt lgkmcnt(5)
; #define LAS __attribute__((address_space(3)))
; __device__ __forceinline__ void phase_scan(CParams& P, LAS unsigned char* lds) {
;     ...
;             f32x4 Ar0, Ar1, Aw0, Aw1, Ak0, Ak1, Aq0, Aq1, Ab0, Ab1, Br0, Br1, Bw0, Bw1, Bk0, Bk1, Bq0, Bq1, Bb0, Bb1; float Avv, Bvv;
; #pragma unroll 1
;             for (int c = 0; c < NCH; ++c) {
;                 __syncthreads();
;                 const LAS float* base = lf + (c & 1) * BUFF + 8 * oct;
;                 SC_LOAD(A, base);
; #pragma unroll 2
;                 for (int j = 0; j < CH; j += 2) { const LAS float* sp = base + j * STEPF;
;                     SC_LOAD(B, sp + STEPF); SC_STEP(A);
;                     SC_LOAD(A, sp + 2 * STEPF);
;                     SC_STEP(B); }
	v_pk_mul_f32 v[78:79], v[2:3], v[132:133] op_sel_hi:[1,0]
	v_pk_mul_f32 v[92:93], v[2:3], v[46:47] op_sel_hi:[1,0]
	v_pk_fma_f32 v[78:79], v[4:5], v[132:133], v[78:79] op_sel:[0,1,0] op_sel_hi:[1,1,1]
	v_pk_fma_f32 v[92:93], v[4:5], v[46:47], v[92:93] op_sel:[0,1,0] op_sel_hi:[1,1,1]
	v_pk_fma_f32 v[78:79], v[6:7], v[134:135], v[78:79] op_sel_hi:[1,0,1]
	v_pk_fma_f32 v[92:93], v[6:7], v[48:49], v[92:93] op_sel_hi:[1,0,1]
	v_pk_fma_f32 v[78:79], v[8:9], v[134:135], v[78:79] op_sel:[0,1,0] op_sel_hi:[1,1,1]
	v_pk_mul_f32 v[82:83], v[74:75], v[140:141] op_sel_hi:[1,0]
	v_pk_fma_f32 v[92:93], v[8:9], v[48:49], v[92:93] op_sel:[0,1,0] op_sel_hi:[1,1,1]
	v_pk_mul_f32 v[84:85], v[74:75], v[140:141] op_sel:[0,1] op_sel_hi:[1,1]
	v_add_f32_dpp v78, v78, v78 quad_perm:[1,0,3,2] row_mask:0xf bank_mask:0xf bound_ctrl:1
	v_add_f32_dpp v79, v79, v79 quad_perm:[1,0,3,2] row_mask:0xf bank_mask:0xf bound_ctrl:1
	v_pk_mul_f32 v[86:87], v[74:75], v[142:143] op_sel_hi:[1,0]
	ds_read_b128 v[30:33], v100 offset:5120
	v_add_f32_dpp v78, v78, v78 quad_perm:[2,3,0,1] row_mask:0xf bank_mask:0xf bound_ctrl:1
	v_add_f32_dpp v79, v79, v79 quad_perm:[2,3,0,1] row_mask:0xf bank_mask:0xf bound_ctrl:1
	v_pk_mul_f32 v[88:89], v[74:75], v[142:143] op_sel:[0,1] op_sel_hi:[1,1]
	ds_read_b128 v[38:41], v100 offset:5632
	v_add_f32_dpp v78, v78, v78 row_half_mirror row_mask:0xf bank_mask:0xf bound_ctrl:1
	v_add_f32_dpp v79, v79, v79 row_half_mirror row_mask:0xf bank_mask:0xf bound_ctrl:1
	v_pk_fma_f32 v[82:83], v[2:3], v[136:137], v[82:83] op_sel_hi:[1,0,1]
	ds_read_b128 v[34:37], v100 offset:5376
	v_add_f32_dpp v78, v78, v78 row_mirror row_mask:0xf bank_mask:0xf bound_ctrl:1
	v_add_f32_dpp v79, v79, v79 row_mirror row_mask:0xf bank_mask:0xf bound_ctrl:1
	v_pk_fma_f32 v[84:85], v[4:5], v[136:137], v[84:85] op_sel:[0,1,0] op_sel_hi:[1,1,1]
	ds_read_b128 v[42:45], v100 offset:5888
	v_pk_fma_f32 v[86:87], v[6:7], v[138:139], v[86:87] op_sel_hi:[1,0,1]
	ds_read_b128 v[46:49], v100 offset:6144
	v_pk_fma_f32 v[88:89], v[8:9], v[138:139], v[88:89] op_sel:[0,1,0] op_sel_hi:[1,1,1]
	ds_read_b128 v[70:73], v101 offset:32
	v_pk_fma_f32 v[2:3], v[78:79], v[144:145], v[82:83] op_sel_hi:[1,0,1]
	v_pk_fma_f32 v[4:5], v[78:79], v[144:145], v[84:85] op_sel:[0,1,0] op_sel_hi:[1,1,1]
	v_pk_fma_f32 v[6:7], v[78:79], v[146:147], v[86:87] op_sel_hi:[1,0,1]
	v_pk_fma_f32 v[8:9], v[78:79], v[146:147], v[88:89] op_sel:[0,1,0] op_sel_hi:[1,1,1]
	s_waitcnt lgkmcnt(6)
	v_pk_mul_f32 v[78:79], v[2:3], v[10:11] op_sel_hi:[1,0]
	v_pk_mul_f32 v[94:95], v[2:3], v[148:149] op_sel_hi:[1,0]
	v_pk_fma_f32 v[78:79], v[4:5], v[10:11], v[78:79] op_sel:[0,1,0] op_sel_hi:[1,1,1]
	v_pk_fma_f32 v[94:95], v[4:5], v[148:149], v[94:95] op_sel:[0,1,0] op_sel_hi:[1,1,1]
	v_pk_fma_f32 v[78:79], v[6:7], v[12:13], v[78:79] op_sel_hi:[1,0,1]
	v_pk_fma_f32 v[94:95], v[6:7], v[150:151], v[94:95] op_sel_hi:[1,0,1]
	v_pk_fma_f32 v[78:79], v[8:9], v[12:13], v[78:79] op_sel:[0,1,0] op_sel_hi:[1,1,1]
	v_pk_mul_f32 v[82:83], v[76:77], v[18:19] op_sel_hi:[1,0]
	v_pk_fma_f32 v[94:95], v[8:9], v[150:151], v[94:95] op_sel:[0,1,0] op_sel_hi:[1,1,1]
	v_pk_mul_f32 v[84:85], v[76:77], v[18:19] op_sel:[0,1] op_sel_hi:[1,1]
	v_add_f32_dpp v78, v78, v78 quad_perm:[1,0,3,2] row_mask:0xf bank_mask:0xf bound_ctrl:1
	v_add_f32_dpp v79, v79, v79 quad_perm:[1,0,3,2] row_mask:0xf bank_mask:0xf bound_ctrl:1
	v_pk_mul_f32 v[86:87], v[76:77], v[20:21] op_sel_hi:[1,0]
	ds_read_b128 v[132:135], v100 offset:6400
	v_add_f32_dpp v78, v78, v78 quad_perm:[2,3,0,1] row_mask:0xf bank_mask:0xf bound_ctrl:1
	v_add_f32_dpp v79, v79, v79 quad_perm:[2,3,0,1] row_mask:0xf bank_mask:0xf bound_ctrl:1
	v_pk_mul_f32 v[88:89], v[76:77], v[20:21] op_sel:[0,1] op_sel_hi:[1,1]
	ds_read_b128 v[140:143], v100 offset:6912
	v_add_f32_dpp v78, v78, v78 row_half_mirror row_mask:0xf bank_mask:0xf bound_ctrl:1
	v_add_f32_dpp v79, v79, v79 row_half_mirror row_mask:0xf bank_mask:0xf bound_ctrl:1
	v_pk_fma_f32 v[82:83], v[2:3], v[14:15], v[82:83] op_sel_hi:[1,0,1]
	ds_read_b128 v[136:139], v100 offset:6656
	v_add_f32_dpp v78, v78, v78 row_mirror row_mask:0xf bank_mask:0xf bound_ctrl:1
	v_add_f32_dpp v79, v79, v79 row_mirror row_mask:0xf bank_mask:0xf bound_ctrl:1
	v_pk_fma_f32 v[84:85], v[4:5], v[14:15], v[84:85] op_sel:[0,1,0] op_sel_hi:[1,1,1]
	ds_read_b128 v[144:147], v100 offset:7168
	v_pk_fma_f32 v[86:87], v[6:7], v[16:17], v[86:87] op_sel_hi:[1,0,1]
	ds_read_b128 v[148:151], v100 offset:7424
	v_pk_fma_f32 v[88:89], v[8:9], v[16:17], v[88:89] op_sel:[0,1,0] op_sel_hi:[1,1,1]
	v_pk_fma_f32 v[2:3], v[78:79], v[22:23], v[82:83] op_sel_hi:[1,0,1]
	v_pk_fma_f32 v[4:5], v[78:79], v[22:23], v[84:85] op_sel:[0,1,0] op_sel_hi:[1,1,1]
	v_pk_fma_f32 v[6:7], v[78:79], v[24:25], v[86:87] op_sel_hi:[1,0,1]
	v_pk_fma_f32 v[8:9], v[78:79], v[24:25], v[88:89] op_sel:[0,1,0] op_sel_hi:[1,1,1]
	s_waitcnt lgkmcnt(5)
; #define LAS __attribute__((address_space(3)))
; __device__ __forceinline__ void phase_scan(CParams& P, LAS unsigned char* lds) {
;     ...
;             f32x4 Ar0, Ar1, Aw0, Aw1, Ak0, Ak1, Aq0, Aq1, Ab0, Ab1, Br0, Br1, Bw0, Bw1, Bk0, Bk1, Bq0, Bq1, Bb0, Bb1; float Avv, Bvv;
; #pragma unroll 1
;             for (int c = 0; c < NCH; ++c) {
;                 __syncthreads();
;                 const LAS float* base = lf + (c & 1) * BUFF + 8 * oct;
;                 SC_LOAD(A, base);
; #pragma unroll 2
;                 for (int j = 0; j < CH; j += 2) { const LAS float* sp = base + j * STEPF;
;                     SC_LOAD(B, sp + STEPF); SC_STEP(A);
;                     SC_LOAD(A, sp + 2 * STEPF);
;                     SC_STEP(B); }
	v_pk_mul_f32 v[78:79], v[2:3], v[30:31] op_sel_hi:[1,0]
	v_pk_mul_f32 v[96:97], v[2:3], v[26:27] op_sel_hi:[1,0]
	v_pk_fma_f32 v[78:79], v[4:5], v[30:31], v[78:79] op_sel:[0,1,0] op_sel_hi:[1,1,1]
	v_pk_fma_f32 v[96:97], v[4:5], v[26:27], v[96:97] op_sel:[0,1,0] op_sel_hi:[1,1,1]
	v_pk_fma_f32 v[78:79], v[6:7], v[32:33], v[78:79] op_sel_hi:[1,0,1]
	v_pk_fma_f32 v[96:97], v[6:7], v[28:29], v[96:97] op_sel_hi:[1,0,1]
	v_pk_fma_f32 v[78:79], v[8:9], v[32:33], v[78:79] op_sel:[0,1,0] op_sel_hi:[1,1,1]
	v_pk_mul_f32 v[82:83], v[70:71], v[38:39] op_sel_hi:[1,0]
	v_pk_fma_f32 v[96:97], v[8:9], v[28:29], v[96:97] op_sel:[0,1,0] op_sel_hi:[1,1,1]
	v_pk_mul_f32 v[84:85], v[70:71], v[38:39] op_sel:[0,1] op_sel_hi:[1,1]
	v_add_f32_dpp v78, v78, v78 quad_perm:[1,0,3,2] row_mask:0xf bank_mask:0xf bound_ctrl:1
	v_add_f32_dpp v79, v79, v79 quad_perm:[1,0,3,2] row_mask:0xf bank_mask:0xf bound_ctrl:1
	v_pk_mul_f32 v[86:87], v[70:71], v[40:41] op_sel_hi:[1,0]
	ds_read_b128 v[10:13], v100 offset:7680
	v_add_f32_dpp v78, v78, v78 quad_perm:[2,3,0,1] row_mask:0xf bank_mask:0xf bound_ctrl:1
	v_add_f32_dpp v79, v79, v79 quad_perm:[2,3,0,1] row_mask:0xf bank_mask:0xf bound_ctrl:1
	v_pk_mul_f32 v[88:89], v[70:71], v[40:41] op_sel:[0,1] op_sel_hi:[1,1]
	ds_read_b128 v[18:21], v100 offset:8192
	v_add_f32_dpp v78, v78, v78 row_half_mirror row_mask:0xf bank_mask:0xf bound_ctrl:1
	v_add_f32_dpp v79, v79, v79 row_half_mirror row_mask:0xf bank_mask:0xf bound_ctrl:1
	v_pk_fma_f32 v[82:83], v[2:3], v[34:35], v[82:83] op_sel_hi:[1,0,1]
	ds_read_b128 v[14:17], v100 offset:7936
	v_add_f32_dpp v78, v78, v78 row_mirror row_mask:0xf bank_mask:0xf bound_ctrl:1
	v_add_f32_dpp v79, v79, v79 row_mirror row_mask:0xf bank_mask:0xf bound_ctrl:1
	v_pk_fma_f32 v[84:85], v[4:5], v[34:35], v[84:85] op_sel:[0,1,0] op_sel_hi:[1,1,1]
	ds_read_b128 v[22:25], v100 offset:8448
	v_pk_fma_f32 v[86:87], v[6:7], v[36:37], v[86:87] op_sel_hi:[1,0,1]
	ds_read_b128 v[26:29], v100 offset:8704
	v_pk_fma_f32 v[88:89], v[8:9], v[36:37], v[88:89] op_sel:[0,1,0] op_sel_hi:[1,1,1]
	ds_read_b128 v[74:77], v101 offset:48
	v_cndmask_b32_e64 v104, v90, v92, s[50:51]
	v_cndmask_b32_e64 v106, v92, v90, s[50:51]
	v_cndmask_b32_e64 v108, v94, v96, s[50:51]
	v_pk_fma_f32 v[2:3], v[78:79], v[42:43], v[82:83] op_sel_hi:[1,0,1]
	v_pk_fma_f32 v[4:5], v[78:79], v[42:43], v[84:85] op_sel:[0,1,0] op_sel_hi:[1,1,1]
	v_pk_fma_f32 v[6:7], v[78:79], v[44:45], v[86:87] op_sel_hi:[1,0,1]
	v_pk_fma_f32 v[8:9], v[78:79], v[44:45], v[88:89] op_sel:[0,1,0] op_sel_hi:[1,1,1]
	v_cndmask_b32_e64 v110, v96, v94, s[50:51]
	v_cndmask_b32_e64 v105, v91, v93, s[50:51]
	v_cndmask_b32_e64 v107, v93, v91, s[50:51]
	s_waitcnt lgkmcnt(6)
	v_pk_mul_f32 v[78:79], v[2:3], v[132:133] op_sel_hi:[1,0]
	v_pk_mul_f32 v[90:91], v[2:3], v[46:47] op_sel_hi:[1,0]
	v_pk_fma_f32 v[78:79], v[4:5], v[132:133], v[78:79] op_sel:[0,1,0] op_sel_hi:[1,1,1]
	v_pk_fma_f32 v[90:91], v[4:5], v[46:47], v[90:91] op_sel:[0,1,0] op_sel_hi:[1,1,1]
	v_pk_fma_f32 v[78:79], v[6:7], v[134:135], v[78:79] op_sel_hi:[1,0,1]
	v_pk_fma_f32 v[90:91], v[6:7], v[48:49], v[90:91] op_sel_hi:[1,0,1]
	v_pk_fma_f32 v[78:79], v[8:9], v[134:135], v[78:79] op_sel:[0,1,0] op_sel_hi:[1,1,1]
	v_pk_mul_f32 v[82:83], v[72:73], v[140:141] op_sel_hi:[1,0]
	v_pk_fma_f32 v[90:91], v[8:9], v[48:49], v[90:91] op_sel:[0,1,0] op_sel_hi:[1,1,1]
	v_pk_mul_f32 v[84:85], v[72:73], v[140:141] op_sel:[0,1] op_sel_hi:[1,1]
	v_add_f32_dpp v78, v78, v78 quad_perm:[1,0,3,2] row_mask:0xf bank_mask:0xf bound_ctrl:1
	v_add_f32_dpp v79, v79, v79 quad_perm:[1,0,3,2] row_mask:0xf bank_mask:0xf bound_ctrl:1
	v_pk_mul_f32 v[86:87], v[72:73], v[142:143] op_sel_hi:[1,0]
	ds_read_b128 v[30:33], v100 offset:8960
	v_add_f32_dpp v78, v78, v78 quad_perm:[2,3,0,1] row_mask:0xf bank_mask:0xf bound_ctrl:1
	v_add_f32_dpp v79, v79, v79 quad_perm:[2,3,0,1] row_mask:0xf bank_mask:0xf bound_ctrl:1
	v_pk_mul_f32 v[88:89], v[72:73], v[142:143] op_sel:[0,1] op_sel_hi:[1,1]
	ds_read_b128 v[38:41], v100 offset:9472
	v_add_f32_dpp v78, v78, v78 row_half_mirror row_mask:0xf bank_mask:0xf bound_ctrl:1
	v_add_f32_dpp v79, v79, v79 row_half_mirror row_mask:0xf bank_mask:0xf bound_ctrl:1
	v_pk_fma_f32 v[82:83], v[2:3], v[136:137], v[82:83] op_sel_hi:[1,0,1]
	ds_read_b128 v[34:37], v100 offset:9216
	v_add_f32_dpp v78, v78, v78 row_mirror row_mask:0xf bank_mask:0xf bound_ctrl:1
	v_add_f32_dpp v79, v79, v79 row_mirror row_mask:0xf bank_mask:0xf bound_ctrl:1
	v_pk_fma_f32 v[84:85], v[4:5], v[136:137], v[84:85] op_sel:[0,1,0] op_sel_hi:[1,1,1]
	ds_read_b128 v[42:45], v100 offset:9728
	v_pk_fma_f32 v[86:87], v[6:7], v[138:139], v[86:87] op_sel_hi:[1,0,1]
	ds_read_b128 v[46:49], v100 offset:9984
	v_pk_fma_f32 v[88:89], v[8:9], v[138:139], v[88:89] op_sel:[0,1,0] op_sel_hi:[1,1,1]
	v_cndmask_b32_e64 v109, v95, v97, s[50:51]
	v_cndmask_b32_e64 v111, v97, v95, s[50:51]
	v_add_f32_dpp v112, v106, v104 quad_perm:[1,0,3,2] row_mask:0xf bank_mask:0xf bound_ctrl:1
	v_pk_fma_f32 v[2:3], v[78:79], v[144:145], v[82:83] op_sel_hi:[1,0,1]
	v_pk_fma_f32 v[4:5], v[78:79], v[144:145], v[84:85] op_sel:[0,1,0] op_sel_hi:[1,1,1]
	v_pk_fma_f32 v[6:7], v[78:79], v[146:147], v[86:87] op_sel_hi:[1,0,1]
	v_pk_fma_f32 v[8:9], v[78:79], v[146:147], v[88:89] op_sel:[0,1,0] op_sel_hi:[1,1,1]
	v_add_f32_dpp v114, v110, v108 quad_perm:[1,0,3,2] row_mask:0xf bank_mask:0xf bound_ctrl:1
	v_add_f32_dpp v113, v107, v105 quad_perm:[1,0,3,2] row_mask:0xf bank_mask:0xf bound_ctrl:1
	v_add_f32_dpp v115, v111, v109 quad_perm:[1,0,3,2] row_mask:0xf bank_mask:0xf bound_ctrl:1
	s_waitcnt lgkmcnt(5)
; #define LAS __attribute__((address_space(3)))
; __device__ __forceinline__ void phase_scan(CParams& P, LAS unsigned char* lds) {
;     ...
;             f32x4 Ar0, Ar1, Aw0, Aw1, Ak0, Ak1, Aq0, Aq1, Ab0, Ab1, Br0, Br1, Bw0, Bw1, Bk0, Bk1, Bq0, Bq1, Bb0, Bb1; float Avv, Bvv;
; #pragma unroll 1
;             for (int c = 0; c < NCH; ++c) {
;                 __syncthreads();
;                 const LAS float* base = lf + (c & 1) * BUFF + 8 * oct;
;                 SC_LOAD(A, base);
; #pragma unroll 2
;                 for (int j = 0; j < CH; j += 2) { const LAS float* sp = base + j * STEPF;
;                     SC_LOAD(B, sp + STEPF); SC_STEP(A);
;                     SC_LOAD(A, sp + 2 * STEPF);
;                     SC_STEP(B); }
	v_pk_mul_f32 v[78:79], v[2:3], v[10:11] op_sel_hi:[1,0]
	v_pk_mul_f32 v[92:93], v[2:3], v[148:149] op_sel_hi:[1,0]
	v_pk_fma_f32 v[78:79], v[4:5], v[10:11], v[78:79] op_sel:[0,1,0] op_sel_hi:[1,1,1]
	v_pk_fma_f32 v[92:93], v[4:5], v[148:149], v[92:93] op_sel:[0,1,0] op_sel_hi:[1,1,1]
	v_pk_fma_f32 v[78:79], v[6:7], v[12:13], v[78:79] op_sel_hi:[1,0,1]
	v_pk_fma_f32 v[92:93], v[6:7], v[150:151], v[92:93] op_sel_hi:[1,0,1]
	v_pk_fma_f32 v[78:79], v[8:9], v[12:13], v[78:79] op_sel:[0,1,0] op_sel_hi:[1,1,1]
	v_pk_mul_f32 v[82:83], v[74:75], v[18:19] op_sel_hi:[1,0]
	v_pk_fma_f32 v[92:93], v[8:9], v[150:151], v[92:93] op_sel:[0,1,0] op_sel_hi:[1,1,1]
	v_pk_mul_f32 v[84:85], v[74:75], v[18:19] op_sel:[0,1] op_sel_hi:[1,1]
	v_add_f32_dpp v78, v78, v78 quad_perm:[1,0,3,2] row_mask:0xf bank_mask:0xf bound_ctrl:1
	v_add_f32_dpp v79, v79, v79 quad_perm:[1,0,3,2] row_mask:0xf bank_mask:0xf bound_ctrl:1
	v_pk_mul_f32 v[86:87], v[74:75], v[20:21] op_sel_hi:[1,0]
	ds_read_b128 v[132:135], v100 offset:10240
	v_add_f32_dpp v78, v78, v78 quad_perm:[2,3,0,1] row_mask:0xf bank_mask:0xf bound_ctrl:1
	v_add_f32_dpp v79, v79, v79 quad_perm:[2,3,0,1] row_mask:0xf bank_mask:0xf bound_ctrl:1
	v_pk_mul_f32 v[88:89], v[74:75], v[20:21] op_sel:[0,1] op_sel_hi:[1,1]
	ds_read_b128 v[140:143], v100 offset:10752
	v_add_f32_dpp v78, v78, v78 row_half_mirror row_mask:0xf bank_mask:0xf bound_ctrl:1
	v_add_f32_dpp v79, v79, v79 row_half_mirror row_mask:0xf bank_mask:0xf bound_ctrl:1
	v_pk_fma_f32 v[82:83], v[2:3], v[14:15], v[82:83] op_sel_hi:[1,0,1]
	ds_read_b128 v[136:139], v100 offset:10496
	v_add_f32_dpp v78, v78, v78 row_mirror row_mask:0xf bank_mask:0xf bound_ctrl:1
	v_add_f32_dpp v79, v79, v79 row_mirror row_mask:0xf bank_mask:0xf bound_ctrl:1
	v_pk_fma_f32 v[84:85], v[4:5], v[14:15], v[84:85] op_sel:[0,1,0] op_sel_hi:[1,1,1]
	ds_read_b128 v[144:147], v100 offset:11008
	v_pk_fma_f32 v[86:87], v[6:7], v[16:17], v[86:87] op_sel_hi:[1,0,1]
	ds_read_b128 v[148:151], v100 offset:11264
	v_pk_fma_f32 v[88:89], v[8:9], v[16:17], v[88:89] op_sel:[0,1,0] op_sel_hi:[1,1,1]
	ds_read_b128 v[70:73], v101 offset:64
	v_cndmask_b32_e64 v116, v112, v114, s[52:53]
	v_cndmask_b32_e64 v118, v114, v112, s[52:53]
	v_cndmask_b32_e64 v117, v113, v115, s[52:53]
	v_pk_fma_f32 v[2:3], v[78:79], v[22:23], v[82:83] op_sel_hi:[1,0,1]
	v_pk_fma_f32 v[4:5], v[78:79], v[22:23], v[84:85] op_sel:[0,1,0] op_sel_hi:[1,1,1]
	v_pk_fma_f32 v[6:7], v[78:79], v[24:25], v[86:87] op_sel_hi:[1,0,1]
	v_pk_fma_f32 v[8:9], v[78:79], v[24:25], v[88:89] op_sel:[0,1,0] op_sel_hi:[1,1,1]
	v_cndmask_b32_e64 v119, v115, v113, s[52:53]
	v_add_f32_dpp v120, v118, v116 quad_perm:[2,3,0,1] row_mask:0xf bank_mask:0xf bound_ctrl:1
	s_nop 0
	v_add_f32_dpp v121, v119, v117 quad_perm:[2,3,0,1] row_mask:0xf bank_mask:0xf bound_ctrl:1
	s_waitcnt lgkmcnt(6)
	v_pk_mul_f32 v[78:79], v[2:3], v[30:31] op_sel_hi:[1,0]
	v_pk_mul_f32 v[94:95], v[2:3], v[26:27] op_sel_hi:[1,0]
	v_pk_fma_f32 v[78:79], v[4:5], v[30:31], v[78:79] op_sel:[0,1,0] op_sel_hi:[1,1,1]
	v_pk_fma_f32 v[94:95], v[4:5], v[26:27], v[94:95] op_sel:[0,1,0] op_sel_hi:[1,1,1]
	v_pk_fma_f32 v[78:79], v[6:7], v[32:33], v[78:79] op_sel_hi:[1,0,1]
	v_pk_fma_f32 v[94:95], v[6:7], v[28:29], v[94:95] op_sel_hi:[1,0,1]
	v_pk_fma_f32 v[78:79], v[8:9], v[32:33], v[78:79] op_sel:[0,1,0] op_sel_hi:[1,1,1]
	v_pk_mul_f32 v[82:83], v[76:77], v[38:39] op_sel_hi:[1,0]
	v_pk_fma_f32 v[94:95], v[8:9], v[28:29], v[94:95] op_sel:[0,1,0] op_sel_hi:[1,1,1]
	v_pk_mul_f32 v[84:85], v[76:77], v[38:39] op_sel:[0,1] op_sel_hi:[1,1]
	v_add_f32_dpp v78, v78, v78 quad_perm:[1,0,3,2] row_mask:0xf bank_mask:0xf bound_ctrl:1
	v_add_f32_dpp v79, v79, v79 quad_perm:[1,0,3,2] row_mask:0xf bank_mask:0xf bound_ctrl:1
	v_pk_mul_f32 v[86:87], v[76:77], v[40:41] op_sel_hi:[1,0]
	ds_read_b128 v[10:13], v100 offset:11520
	v_add_f32_dpp v78, v78, v78 quad_perm:[2,3,0,1] row_mask:0xf bank_mask:0xf bound_ctrl:1
	v_add_f32_dpp v79, v79, v79 quad_perm:[2,3,0,1] row_mask:0xf bank_mask:0xf bound_ctrl:1
	v_pk_mul_f32 v[88:89], v[76:77], v[40:41] op_sel:[0,1] op_sel_hi:[1,1]
	ds_read_b128 v[18:21], v100 offset:12032
	v_add_f32_dpp v78, v78, v78 row_half_mirror row_mask:0xf bank_mask:0xf bound_ctrl:1
	v_add_f32_dpp v79, v79, v79 row_half_mirror row_mask:0xf bank_mask:0xf bound_ctrl:1
	v_pk_fma_f32 v[82:83], v[2:3], v[34:35], v[82:83] op_sel_hi:[1,0,1]
	ds_read_b128 v[14:17], v100 offset:11776
	v_add_f32_dpp v78, v78, v78 row_mirror row_mask:0xf bank_mask:0xf bound_ctrl:1
	v_add_f32_dpp v79, v79, v79 row_mirror row_mask:0xf bank_mask:0xf bound_ctrl:1
	v_pk_fma_f32 v[84:85], v[4:5], v[34:35], v[84:85] op_sel:[0,1,0] op_sel_hi:[1,1,1]
	ds_read_b128 v[22:25], v100 offset:12288
	v_pk_fma_f32 v[86:87], v[6:7], v[36:37], v[86:87] op_sel_hi:[1,0,1]
	ds_read_b128 v[26:29], v100 offset:12544
	v_pk_fma_f32 v[88:89], v[8:9], v[36:37], v[88:89] op_sel:[0,1,0] op_sel_hi:[1,1,1]
	v_add_f32_dpp v120, v120, v120 row_ror:4 row_mask:0xf bank_mask:0xf bound_ctrl:1
	v_add_f32_dpp v121, v121, v121 row_ror:4 row_mask:0xf bank_mask:0xf bound_ctrl:1
	s_nop 0
	v_add_f32_dpp v120, v120, v120 row_ror:8 row_mask:0xf bank_mask:0xf bound_ctrl:1
	v_pk_fma_f32 v[2:3], v[78:79], v[42:43], v[82:83] op_sel_hi:[1,0,1]
	v_pk_fma_f32 v[4:5], v[78:79], v[42:43], v[84:85] op_sel:[0,1,0] op_sel_hi:[1,1,1]
	v_pk_fma_f32 v[6:7], v[78:79], v[44:45], v[86:87] op_sel_hi:[1,0,1]
	v_pk_fma_f32 v[8:9], v[78:79], v[44:45], v[88:89] op_sel:[0,1,0] op_sel_hi:[1,1,1]
	v_add_f32_dpp v121, v121, v121 row_ror:8 row_mask:0xf bank_mask:0xf bound_ctrl:1
	global_store_dwordx2 v102, v[120:121], s[10:11]
	v_add_u32_e32 v102, s13, v102
	s_waitcnt lgkmcnt(5)
; #define LAS __attribute__((address_space(3)))
; __device__ __forceinline__ void phase_scan(CParams& P, LAS unsigned char* lds) {
;     ...
;             f32x4 Ar0, Ar1, Aw0, Aw1, Ak0, Ak1, Aq0, Aq1, Ab0, Ab1, Br0, Br1, Bw0, Bw1, Bk0, Bk1, Bq0, Bq1, Bb0, Bb1; float Avv, Bvv;
; #pragma unroll 1
;             for (int c = 0; c < NCH; ++c) {
;                 __syncthreads();
;                 const LAS float* base = lf + (c & 1) * BUFF + 8 * oct;
;                 SC_LOAD(A, base);
; #pragma unroll 2
;                 for (int j = 0; j < CH; j += 2) { const LAS float* sp = base + j * STEPF;
;                     SC_LOAD(B, sp + STEPF); SC_STEP(A);
;                     SC_LOAD(A, sp + 2 * STEPF);
;                     SC_STEP(B); }
	v_pk_mul_f32 v[78:79], v[2:3], v[132:133] op_sel_hi:[1,0]
	v_pk_mul_f32 v[96:97], v[2:3], v[46:47] op_sel_hi:[1,0]
	v_pk_fma_f32 v[78:79], v[4:5], v[132:133], v[78:79] op_sel:[0,1,0] op_sel_hi:[1,1,1]
	v_pk_fma_f32 v[96:97], v[4:5], v[46:47], v[96:97] op_sel:[0,1,0] op_sel_hi:[1,1,1]
	v_pk_fma_f32 v[78:79], v[6:7], v[134:135], v[78:79] op_sel_hi:[1,0,1]
	v_pk_fma_f32 v[96:97], v[6:7], v[48:49], v[96:97] op_sel_hi:[1,0,1]
	v_pk_fma_f32 v[78:79], v[8:9], v[134:135], v[78:79] op_sel:[0,1,0] op_sel_hi:[1,1,1]
	v_pk_mul_f32 v[82:83], v[70:71], v[140:141] op_sel_hi:[1,0]
	v_pk_fma_f32 v[96:97], v[8:9], v[48:49], v[96:97] op_sel:[0,1,0] op_sel_hi:[1,1,1]
	v_pk_mul_f32 v[84:85], v[70:71], v[140:141] op_sel:[0,1] op_sel_hi:[1,1]
	v_add_f32_dpp v78, v78, v78 quad_perm:[1,0,3,2] row_mask:0xf bank_mask:0xf bound_ctrl:1
	v_add_f32_dpp v79, v79, v79 quad_perm:[1,0,3,2] row_mask:0xf bank_mask:0xf bound_ctrl:1
	v_pk_mul_f32 v[86:87], v[70:71], v[142:143] op_sel_hi:[1,0]
	ds_read_b128 v[30:33], v100 offset:12800
	v_add_f32_dpp v78, v78, v78 quad_perm:[2,3,0,1] row_mask:0xf bank_mask:0xf bound_ctrl:1
	v_add_f32_dpp v79, v79, v79 quad_perm:[2,3,0,1] row_mask:0xf bank_mask:0xf bound_ctrl:1
	v_pk_mul_f32 v[88:89], v[70:71], v[142:143] op_sel:[0,1] op_sel_hi:[1,1]
	ds_read_b128 v[38:41], v100 offset:13312
	v_add_f32_dpp v78, v78, v78 row_half_mirror row_mask:0xf bank_mask:0xf bound_ctrl:1
	v_add_f32_dpp v79, v79, v79 row_half_mirror row_mask:0xf bank_mask:0xf bound_ctrl:1
	v_pk_fma_f32 v[82:83], v[2:3], v[136:137], v[82:83] op_sel_hi:[1,0,1]
	ds_read_b128 v[34:37], v100 offset:13056
	v_add_f32_dpp v78, v78, v78 row_mirror row_mask:0xf bank_mask:0xf bound_ctrl:1
	v_add_f32_dpp v79, v79, v79 row_mirror row_mask:0xf bank_mask:0xf bound_ctrl:1
	v_pk_fma_f32 v[84:85], v[4:5], v[136:137], v[84:85] op_sel:[0,1,0] op_sel_hi:[1,1,1]
	ds_read_b128 v[42:45], v100 offset:13568
	v_pk_fma_f32 v[86:87], v[6:7], v[138:139], v[86:87] op_sel_hi:[1,0,1]
	ds_read_b128 v[46:49], v100 offset:13824
	v_pk_fma_f32 v[88:89], v[8:9], v[138:139], v[88:89] op_sel:[0,1,0] op_sel_hi:[1,1,1]
	ds_read_b128 v[74:77], v101 offset:80
	v_cndmask_b32_e64 v104, v90, v92, s[50:51]
	v_cndmask_b32_e64 v106, v92, v90, s[50:51]
	v_cndmask_b32_e64 v108, v94, v96, s[50:51]
	v_pk_fma_f32 v[2:3], v[78:79], v[144:145], v[82:83] op_sel_hi:[1,0,1]
	v_pk_fma_f32 v[4:5], v[78:79], v[144:145], v[84:85] op_sel:[0,1,0] op_sel_hi:[1,1,1]
	v_pk_fma_f32 v[6:7], v[78:79], v[146:147], v[86:87] op_sel_hi:[1,0,1]
	v_pk_fma_f32 v[8:9], v[78:79], v[146:147], v[88:89] op_sel:[0,1,0] op_sel_hi:[1,1,1]
	v_cndmask_b32_e64 v110, v96, v94, s[50:51]
	v_cndmask_b32_e64 v105, v91, v93, s[50:51]
	v_cndmask_b32_e64 v107, v93, v91, s[50:51]
	s_waitcnt lgkmcnt(6)
	v_pk_mul_f32 v[78:79], v[2:3], v[10:11] op_sel_hi:[1,0]
	v_pk_mul_f32 v[90:91], v[2:3], v[148:149] op_sel_hi:[1,0]
	v_pk_fma_f32 v[78:79], v[4:5], v[10:11], v[78:79] op_sel:[0,1,0] op_sel_hi:[1,1,1]
	v_pk_fma_f32 v[90:91], v[4:5], v[148:149], v[90:91] op_sel:[0,1,0] op_sel_hi:[1,1,1]
	v_pk_fma_f32 v[78:79], v[6:7], v[12:13], v[78:79] op_sel_hi:[1,0,1]
	v_pk_fma_f32 v[90:91], v[6:7], v[150:151], v[90:91] op_sel_hi:[1,0,1]
	v_pk_fma_f32 v[78:79], v[8:9], v[12:13], v[78:79] op_sel:[0,1,0] op_sel_hi:[1,1,1]
	v_pk_mul_f32 v[82:83], v[72:73], v[18:19] op_sel_hi:[1,0]
	v_pk_fma_f32 v[90:91], v[8:9], v[150:151], v[90:91] op_sel:[0,1,0] op_sel_hi:[1,1,1]
	v_pk_mul_f32 v[84:85], v[72:73], v[18:19] op_sel:[0,1] op_sel_hi:[1,1]
	v_add_f32_dpp v78, v78, v78 quad_perm:[1,0,3,2] row_mask:0xf bank_mask:0xf bound_ctrl:1
	v_add_f32_dpp v79, v79, v79 quad_perm:[1,0,3,2] row_mask:0xf bank_mask:0xf bound_ctrl:1
	v_pk_mul_f32 v[86:87], v[72:73], v[20:21] op_sel_hi:[1,0]
	ds_read_b128 v[132:135], v100 offset:14080
	v_add_f32_dpp v78, v78, v78 quad_perm:[2,3,0,1] row_mask:0xf bank_mask:0xf bound_ctrl:1
	v_add_f32_dpp v79, v79, v79 quad_perm:[2,3,0,1] row_mask:0xf bank_mask:0xf bound_ctrl:1
	v_pk_mul_f32 v[88:89], v[72:73], v[20:21] op_sel:[0,1] op_sel_hi:[1,1]
	ds_read_b128 v[140:143], v100 offset:14592
	v_add_f32_dpp v78, v78, v78 row_half_mirror row_mask:0xf bank_mask:0xf bound_ctrl:1
	v_add_f32_dpp v79, v79, v79 row_half_mirror row_mask:0xf bank_mask:0xf bound_ctrl:1
	v_pk_fma_f32 v[82:83], v[2:3], v[14:15], v[82:83] op_sel_hi:[1,0,1]
	ds_read_b128 v[136:139], v100 offset:14336
	v_add_f32_dpp v78, v78, v78 row_mirror row_mask:0xf bank_mask:0xf bound_ctrl:1
	v_add_f32_dpp v79, v79, v79 row_mirror row_mask:0xf bank_mask:0xf bound_ctrl:1
	v_pk_fma_f32 v[84:85], v[4:5], v[14:15], v[84:85] op_sel:[0,1,0] op_sel_hi:[1,1,1]
	ds_read_b128 v[144:147], v100 offset:14848
	v_pk_fma_f32 v[86:87], v[6:7], v[16:17], v[86:87] op_sel_hi:[1,0,1]
	ds_read_b128 v[148:151], v100 offset:15104
	v_pk_fma_f32 v[88:89], v[8:9], v[16:17], v[88:89] op_sel:[0,1,0] op_sel_hi:[1,1,1]
	v_cndmask_b32_e64 v109, v95, v97, s[50:51]
	v_cndmask_b32_e64 v111, v97, v95, s[50:51]
	v_add_f32_dpp v112, v106, v104 quad_perm:[1,0,3,2] row_mask:0xf bank_mask:0xf bound_ctrl:1
	v_pk_fma_f32 v[2:3], v[78:79], v[22:23], v[82:83] op_sel_hi:[1,0,1]
	v_pk_fma_f32 v[4:5], v[78:79], v[22:23], v[84:85] op_sel:[0,1,0] op_sel_hi:[1,1,1]
	v_pk_fma_f32 v[6:7], v[78:79], v[24:25], v[86:87] op_sel_hi:[1,0,1]
	v_pk_fma_f32 v[8:9], v[78:79], v[24:25], v[88:89] op_sel:[0,1,0] op_sel_hi:[1,1,1]
	v_add_f32_dpp v114, v110, v108 quad_perm:[1,0,3,2] row_mask:0xf bank_mask:0xf bound_ctrl:1
	v_add_f32_dpp v113, v107, v105 quad_perm:[1,0,3,2] row_mask:0xf bank_mask:0xf bound_ctrl:1
	v_add_f32_dpp v115, v111, v109 quad_perm:[1,0,3,2] row_mask:0xf bank_mask:0xf bound_ctrl:1
	s_waitcnt lgkmcnt(5)
; #define LAS __attribute__((address_space(3)))
; __device__ __forceinline__ void phase_scan(CParams& P, LAS unsigned char* lds) {
;     ...
;             f32x4 Ar0, Ar1, Aw0, Aw1, Ak0, Ak1, Aq0, Aq1, Ab0, Ab1, Br0, Br1, Bw0, Bw1, Bk0, Bk1, Bq0, Bq1, Bb0, Bb1; float Avv, Bvv;
; #pragma unroll 1
;             for (int c = 0; c < NCH; ++c) {
;                 __syncthreads();
;                 const LAS float* base = lf + (c & 1) * BUFF + 8 * oct;
;                 SC_LOAD(A, base);
; #pragma unroll 2
;                 for (int j = 0; j < CH; j += 2) { const LAS float* sp = base + j * STEPF;
;                     SC_LOAD(B, sp + STEPF); SC_STEP(A);
;                     SC_LOAD(A, sp + 2 * STEPF);
;                     SC_STEP(B); }
	v_pk_mul_f32 v[78:79], v[2:3], v[30:31] op_sel_hi:[1,0]
	v_pk_mul_f32 v[92:93], v[2:3], v[26:27] op_sel_hi:[1,0]
	v_pk_fma_f32 v[78:79], v[4:5], v[30:31], v[78:79] op_sel:[0,1,0] op_sel_hi:[1,1,1]
	v_pk_fma_f32 v[92:93], v[4:5], v[26:27], v[92:93] op_sel:[0,1,0] op_sel_hi:[1,1,1]
	v_pk_fma_f32 v[78:79], v[6:7], v[32:33], v[78:79] op_sel_hi:[1,0,1]
	v_pk_fma_f32 v[92:93], v[6:7], v[28:29], v[92:93] op_sel_hi:[1,0,1]
	v_pk_fma_f32 v[78:79], v[8:9], v[32:33], v[78:79] op_sel:[0,1,0] op_sel_hi:[1,1,1]
	v_pk_mul_f32 v[82:83], v[74:75], v[38:39] op_sel_hi:[1,0]
	v_pk_fma_f32 v[92:93], v[8:9], v[28:29], v[92:93] op_sel:[0,1,0] op_sel_hi:[1,1,1]
	v_pk_mul_f32 v[84:85], v[74:75], v[38:39] op_sel:[0,1] op_sel_hi:[1,1]
	v_add_f32_dpp v78, v78, v78 quad_perm:[1,0,3,2] row_mask:0xf bank_mask:0xf bound_ctrl:1
	v_add_f32_dpp v79, v79, v79 quad_perm:[1,0,3,2] row_mask:0xf bank_mask:0xf bound_ctrl:1
	v_pk_mul_f32 v[86:87], v[74:75], v[40:41] op_sel_hi:[1,0]
	ds_read_b128 v[10:13], v100 offset:15360
	v_add_f32_dpp v78, v78, v78 quad_perm:[2,3,0,1] row_mask:0xf bank_mask:0xf bound_ctrl:1
	v_add_f32_dpp v79, v79, v79 quad_perm:[2,3,0,1] row_mask:0xf bank_mask:0xf bound_ctrl:1
	v_pk_mul_f32 v[88:89], v[74:75], v[40:41] op_sel:[0,1] op_sel_hi:[1,1]
	ds_read_b128 v[18:21], v100 offset:15872
	v_add_f32_dpp v78, v78, v78 row_half_mirror row_mask:0xf bank_mask:0xf bound_ctrl:1
	v_add_f32_dpp v79, v79, v79 row_half_mirror row_mask:0xf bank_mask:0xf bound_ctrl:1
	v_pk_fma_f32 v[82:83], v[2:3], v[34:35], v[82:83] op_sel_hi:[1,0,1]
	ds_read_b128 v[14:17], v100 offset:15616
	v_add_f32_dpp v78, v78, v78 row_mirror row_mask:0xf bank_mask:0xf bound_ctrl:1
	v_add_f32_dpp v79, v79, v79 row_mirror row_mask:0xf bank_mask:0xf bound_ctrl:1
	v_pk_fma_f32 v[84:85], v[4:5], v[34:35], v[84:85] op_sel:[0,1,0] op_sel_hi:[1,1,1]
	ds_read_b128 v[22:25], v100 offset:16128
	v_pk_fma_f32 v[86:87], v[6:7], v[36:37], v[86:87] op_sel_hi:[1,0,1]
	ds_read_b128 v[26:29], v100 offset:16384
	v_pk_fma_f32 v[88:89], v[8:9], v[36:37], v[88:89] op_sel:[0,1,0] op_sel_hi:[1,1,1]
	ds_read_b128 v[70:73], v101 offset:96
	v_cndmask_b32_e64 v116, v112, v114, s[52:53]
	v_cndmask_b32_e64 v118, v114, v112, s[52:53]
	v_cndmask_b32_e64 v117, v113, v115, s[52:53]
	v_pk_fma_f32 v[2:3], v[78:79], v[42:43], v[82:83] op_sel_hi:[1,0,1]
	v_pk_fma_f32 v[4:5], v[78:79], v[42:43], v[84:85] op_sel:[0,1,0] op_sel_hi:[1,1,1]
	v_pk_fma_f32 v[6:7], v[78:79], v[44:45], v[86:87] op_sel_hi:[1,0,1]
	v_pk_fma_f32 v[8:9], v[78:79], v[44:45], v[88:89] op_sel:[0,1,0] op_sel_hi:[1,1,1]
	v_cndmask_b32_e64 v119, v115, v113, s[52:53]
	v_add_f32_dpp v120, v118, v116 quad_perm:[2,3,0,1] row_mask:0xf bank_mask:0xf bound_ctrl:1
	s_nop 0
	v_add_f32_dpp v121, v119, v117 quad_perm:[2,3,0,1] row_mask:0xf bank_mask:0xf bound_ctrl:1
	s_waitcnt lgkmcnt(6)
	v_pk_mul_f32 v[78:79], v[2:3], v[132:133] op_sel_hi:[1,0]
	v_pk_mul_f32 v[94:95], v[2:3], v[46:47] op_sel_hi:[1,0]
	v_pk_fma_f32 v[78:79], v[4:5], v[132:133], v[78:79] op_sel:[0,1,0] op_sel_hi:[1,1,1]
	v_pk_fma_f32 v[94:95], v[4:5], v[46:47], v[94:95] op_sel:[0,1,0] op_sel_hi:[1,1,1]
	v_pk_fma_f32 v[78:79], v[6:7], v[134:135], v[78:79] op_sel_hi:[1,0,1]
	v_pk_fma_f32 v[94:95], v[6:7], v[48:49], v[94:95] op_sel_hi:[1,0,1]
	v_pk_fma_f32 v[78:79], v[8:9], v[134:135], v[78:79] op_sel:[0,1,0] op_sel_hi:[1,1,1]
	v_pk_mul_f32 v[82:83], v[76:77], v[140:141] op_sel_hi:[1,0]
	v_pk_fma_f32 v[94:95], v[8:9], v[48:49], v[94:95] op_sel:[0,1,0] op_sel_hi:[1,1,1]
	v_pk_mul_f32 v[84:85], v[76:77], v[140:141] op_sel:[0,1] op_sel_hi:[1,1]
	v_add_f32_dpp v78, v78, v78 quad_perm:[1,0,3,2] row_mask:0xf bank_mask:0xf bound_ctrl:1
	v_add_f32_dpp v79, v79, v79 quad_perm:[1,0,3,2] row_mask:0xf bank_mask:0xf bound_ctrl:1
	v_pk_mul_f32 v[86:87], v[76:77], v[142:143] op_sel_hi:[1,0]
	ds_read_b128 v[30:33], v100 offset:16640
	v_add_f32_dpp v78, v78, v78 quad_perm:[2,3,0,1] row_mask:0xf bank_mask:0xf bound_ctrl:1
	v_add_f32_dpp v79, v79, v79 quad_perm:[2,3,0,1] row_mask:0xf bank_mask:0xf bound_ctrl:1
	v_pk_mul_f32 v[88:89], v[76:77], v[142:143] op_sel:[0,1] op_sel_hi:[1,1]
	ds_read_b128 v[38:41], v100 offset:17152
	v_add_f32_dpp v78, v78, v78 row_half_mirror row_mask:0xf bank_mask:0xf bound_ctrl:1
	v_add_f32_dpp v79, v79, v79 row_half_mirror row_mask:0xf bank_mask:0xf bound_ctrl:1
	v_pk_fma_f32 v[82:83], v[2:3], v[136:137], v[82:83] op_sel_hi:[1,0,1]
	ds_read_b128 v[34:37], v100 offset:16896
	v_add_f32_dpp v78, v78, v78 row_mirror row_mask:0xf bank_mask:0xf bound_ctrl:1
	v_add_f32_dpp v79, v79, v79 row_mirror row_mask:0xf bank_mask:0xf bound_ctrl:1
	v_pk_fma_f32 v[84:85], v[4:5], v[136:137], v[84:85] op_sel:[0,1,0] op_sel_hi:[1,1,1]
	ds_read_b128 v[42:45], v100 offset:17408
	v_pk_fma_f32 v[86:87], v[6:7], v[138:139], v[86:87] op_sel_hi:[1,0,1]
	ds_read_b128 v[46:49], v100 offset:17664
	v_pk_fma_f32 v[88:89], v[8:9], v[138:139], v[88:89] op_sel:[0,1,0] op_sel_hi:[1,1,1]
	v_add_f32_dpp v120, v120, v120 row_ror:4 row_mask:0xf bank_mask:0xf bound_ctrl:1
	v_add_f32_dpp v121, v121, v121 row_ror:4 row_mask:0xf bank_mask:0xf bound_ctrl:1
	s_nop 0
	v_add_f32_dpp v120, v120, v120 row_ror:8 row_mask:0xf bank_mask:0xf bound_ctrl:1
	v_pk_fma_f32 v[2:3], v[78:79], v[144:145], v[82:83] op_sel_hi:[1,0,1]
	v_pk_fma_f32 v[4:5], v[78:79], v[144:145], v[84:85] op_sel:[0,1,0] op_sel_hi:[1,1,1]
	v_pk_fma_f32 v[6:7], v[78:79], v[146:147], v[86:87] op_sel_hi:[1,0,1]
	v_pk_fma_f32 v[8:9], v[78:79], v[146:147], v[88:89] op_sel:[0,1,0] op_sel_hi:[1,1,1]
	v_add_f32_dpp v121, v121, v121 row_ror:8 row_mask:0xf bank_mask:0xf bound_ctrl:1
	global_store_dwordx2 v102, v[120:121], s[10:11]
	v_add_u32_e32 v102, s13, v102
	s_waitcnt lgkmcnt(5)
; #define LAS __attribute__((address_space(3)))
; __device__ __forceinline__ void phase_scan(CParams& P, LAS unsigned char* lds) {
;     ...
;             f32x4 Ar0, Ar1, Aw0, Aw1, Ak0, Ak1, Aq0, Aq1, Ab0, Ab1, Br0, Br1, Bw0, Bw1, Bk0, Bk1, Bq0, Bq1, Bb0, Bb1; float Avv, Bvv;
; #pragma unroll 1
;             for (int c = 0; c < NCH; ++c) {
;                 __syncthreads();
;                 const LAS float* base = lf + (c & 1) * BUFF + 8 * oct;
;                 SC_LOAD(A, base);
; #pragma unroll 2
;                 for (int j = 0; j < CH; j += 2) { const LAS float* sp = base + j * STEPF;
;                     SC_LOAD(B, sp + STEPF); SC_STEP(A);
;                     SC_LOAD(A, sp + 2 * STEPF);
;                     SC_STEP(B); }
	v_pk_mul_f32 v[78:79], v[2:3], v[10:11] op_sel_hi:[1,0]
	v_pk_mul_f32 v[96:97], v[2:3], v[148:149] op_sel_hi:[1,0]
	v_pk_fma_f32 v[78:79], v[4:5], v[10:11], v[78:79] op_sel:[0,1,0] op_sel_hi:[1,1,1]
	v_pk_fma_f32 v[96:97], v[4:5], v[148:149], v[96:97] op_sel:[0,1,0] op_sel_hi:[1,1,1]
	v_pk_fma_f32 v[78:79], v[6:7], v[12:13], v[78:79] op_sel_hi:[1,0,1]
	v_pk_fma_f32 v[96:97], v[6:7], v[150:151], v[96:97] op_sel_hi:[1,0,1]
	v_pk_fma_f32 v[78:79], v[8:9], v[12:13], v[78:79] op_sel:[0,1,0] op_sel_hi:[1,1,1]
	v_pk_mul_f32 v[82:83], v[70:71], v[18:19] op_sel_hi:[1,0]
	v_pk_fma_f32 v[96:97], v[8:9], v[150:151], v[96:97] op_sel:[0,1,0] op_sel_hi:[1,1,1]
	v_pk_mul_f32 v[84:85], v[70:71], v[18:19] op_sel:[0,1] op_sel_hi:[1,1]
	v_add_f32_dpp v78, v78, v78 quad_perm:[1,0,3,2] row_mask:0xf bank_mask:0xf bound_ctrl:1
	v_add_f32_dpp v79, v79, v79 quad_perm:[1,0,3,2] row_mask:0xf bank_mask:0xf bound_ctrl:1
	v_pk_mul_f32 v[86:87], v[70:71], v[20:21] op_sel_hi:[1,0]
	ds_read_b128 v[132:135], v100 offset:17920
	v_add_f32_dpp v78, v78, v78 quad_perm:[2,3,0,1] row_mask:0xf bank_mask:0xf bound_ctrl:1
	v_add_f32_dpp v79, v79, v79 quad_perm:[2,3,0,1] row_mask:0xf bank_mask:0xf bound_ctrl:1
	v_pk_mul_f32 v[88:89], v[70:71], v[20:21] op_sel:[0,1] op_sel_hi:[1,1]
	ds_read_b128 v[140:143], v100 offset:18432
	v_add_f32_dpp v78, v78, v78 row_half_mirror row_mask:0xf bank_mask:0xf bound_ctrl:1
	v_add_f32_dpp v79, v79, v79 row_half_mirror row_mask:0xf bank_mask:0xf bound_ctrl:1
	v_pk_fma_f32 v[82:83], v[2:3], v[14:15], v[82:83] op_sel_hi:[1,0,1]
	ds_read_b128 v[136:139], v100 offset:18176
	v_add_f32_dpp v78, v78, v78 row_mirror row_mask:0xf bank_mask:0xf bound_ctrl:1
	v_add_f32_dpp v79, v79, v79 row_mirror row_mask:0xf bank_mask:0xf bound_ctrl:1
	v_pk_fma_f32 v[84:85], v[4:5], v[14:15], v[84:85] op_sel:[0,1,0] op_sel_hi:[1,1,1]
	ds_read_b128 v[144:147], v100 offset:18688
	v_pk_fma_f32 v[86:87], v[6:7], v[16:17], v[86:87] op_sel_hi:[1,0,1]
	ds_read_b128 v[148:151], v100 offset:18944
	v_pk_fma_f32 v[88:89], v[8:9], v[16:17], v[88:89] op_sel:[0,1,0] op_sel_hi:[1,1,1]
	ds_read_b128 v[74:77], v101 offset:112
	v_cndmask_b32_e64 v104, v90, v92, s[50:51]
	v_cndmask_b32_e64 v106, v92, v90, s[50:51]
	v_cndmask_b32_e64 v108, v94, v96, s[50:51]
	v_pk_fma_f32 v[2:3], v[78:79], v[22:23], v[82:83] op_sel_hi:[1,0,1]
	v_pk_fma_f32 v[4:5], v[78:79], v[22:23], v[84:85] op_sel:[0,1,0] op_sel_hi:[1,1,1]
	v_pk_fma_f32 v[6:7], v[78:79], v[24:25], v[86:87] op_sel_hi:[1,0,1]
	v_pk_fma_f32 v[8:9], v[78:79], v[24:25], v[88:89] op_sel:[0,1,0] op_sel_hi:[1,1,1]
	v_cndmask_b32_e64 v110, v96, v94, s[50:51]
	v_cndmask_b32_e64 v105, v91, v93, s[50:51]
	v_cndmask_b32_e64 v107, v93, v91, s[50:51]
	s_waitcnt lgkmcnt(6)
	v_pk_mul_f32 v[78:79], v[2:3], v[30:31] op_sel_hi:[1,0]
	v_pk_mul_f32 v[90:91], v[2:3], v[26:27] op_sel_hi:[1,0]
	v_pk_fma_f32 v[78:79], v[4:5], v[30:31], v[78:79] op_sel:[0,1,0] op_sel_hi:[1,1,1]
	v_pk_fma_f32 v[90:91], v[4:5], v[26:27], v[90:91] op_sel:[0,1,0] op_sel_hi:[1,1,1]
	v_pk_fma_f32 v[78:79], v[6:7], v[32:33], v[78:79] op_sel_hi:[1,0,1]
	v_pk_fma_f32 v[90:91], v[6:7], v[28:29], v[90:91] op_sel_hi:[1,0,1]
	v_pk_fma_f32 v[78:79], v[8:9], v[32:33], v[78:79] op_sel:[0,1,0] op_sel_hi:[1,1,1]
	v_pk_mul_f32 v[82:83], v[72:73], v[38:39] op_sel_hi:[1,0]
	v_pk_fma_f32 v[90:91], v[8:9], v[28:29], v[90:91] op_sel:[0,1,0] op_sel_hi:[1,1,1]
	v_pk_mul_f32 v[84:85], v[72:73], v[38:39] op_sel:[0,1] op_sel_hi:[1,1]
	v_add_f32_dpp v78, v78, v78 quad_perm:[1,0,3,2] row_mask:0xf bank_mask:0xf bound_ctrl:1
	v_add_f32_dpp v79, v79, v79 quad_perm:[1,0,3,2] row_mask:0xf bank_mask:0xf bound_ctrl:1
	v_pk_mul_f32 v[86:87], v[72:73], v[40:41] op_sel_hi:[1,0]
	ds_read_b128 v[10:13], v100 offset:19200
	v_add_f32_dpp v78, v78, v78 quad_perm:[2,3,0,1] row_mask:0xf bank_mask:0xf bound_ctrl:1
	v_add_f32_dpp v79, v79, v79 quad_perm:[2,3,0,1] row_mask:0xf bank_mask:0xf bound_ctrl:1
	v_pk_mul_f32 v[88:89], v[72:73], v[40:41] op_sel:[0,1] op_sel_hi:[1,1]
	ds_read_b128 v[18:21], v100 offset:19712
	v_add_f32_dpp v78, v78, v78 row_half_mirror row_mask:0xf bank_mask:0xf bound_ctrl:1
	v_add_f32_dpp v79, v79, v79 row_half_mirror row_mask:0xf bank_mask:0xf bound_ctrl:1
	v_pk_fma_f32 v[82:83], v[2:3], v[34:35], v[82:83] op_sel_hi:[1,0,1]
	ds_read_b128 v[14:17], v100 offset:19456
	v_add_f32_dpp v78, v78, v78 row_mirror row_mask:0xf bank_mask:0xf bound_ctrl:1
	v_add_f32_dpp v79, v79, v79 row_mirror row_mask:0xf bank_mask:0xf bound_ctrl:1
	v_pk_fma_f32 v[84:85], v[4:5], v[34:35], v[84:85] op_sel:[0,1,0] op_sel_hi:[1,1,1]
	ds_read_b128 v[22:25], v100 offset:19968
	v_pk_fma_f32 v[86:87], v[6:7], v[36:37], v[86:87] op_sel_hi:[1,0,1]
	ds_read_b128 v[26:29], v100 offset:20224
	v_pk_fma_f32 v[88:89], v[8:9], v[36:37], v[88:89] op_sel:[0,1,0] op_sel_hi:[1,1,1]
	v_cndmask_b32_e64 v109, v95, v97, s[50:51]
	v_cndmask_b32_e64 v111, v97, v95, s[50:51]
	v_add_f32_dpp v112, v106, v104 quad_perm:[1,0,3,2] row_mask:0xf bank_mask:0xf bound_ctrl:1
	v_pk_fma_f32 v[2:3], v[78:79], v[42:43], v[82:83] op_sel_hi:[1,0,1]
	v_pk_fma_f32 v[4:5], v[78:79], v[42:43], v[84:85] op_sel:[0,1,0] op_sel_hi:[1,1,1]
	v_pk_fma_f32 v[6:7], v[78:79], v[44:45], v[86:87] op_sel_hi:[1,0,1]
	v_pk_fma_f32 v[8:9], v[78:79], v[44:45], v[88:89] op_sel:[0,1,0] op_sel_hi:[1,1,1]
	v_add_f32_dpp v114, v110, v108 quad_perm:[1,0,3,2] row_mask:0xf bank_mask:0xf bound_ctrl:1
	v_add_f32_dpp v113, v107, v105 quad_perm:[1,0,3,2] row_mask:0xf bank_mask:0xf bound_ctrl:1
	v_add_f32_dpp v115, v111, v109 quad_perm:[1,0,3,2] row_mask:0xf bank_mask:0xf bound_ctrl:1
	s_waitcnt lgkmcnt(5)
; #define LAS __attribute__((address_space(3)))
; __device__ __forceinline__ void phase_scan(CParams& P, LAS unsigned char* lds) {
;     ...
;             f32x4 Ar0, Ar1, Aw0, Aw1, Ak0, Ak1, Aq0, Aq1, Ab0, Ab1, Br0, Br1, Bw0, Bw1, Bk0, Bk1, Bq0, Bq1, Bb0, Bb1; float Avv, Bvv;
; #pragma unroll 1
;             for (int c = 0; c < NCH; ++c) {
;                 __syncthreads();
;                 const LAS float* base = lf + (c & 1) * BUFF + 8 * oct;
;                 SC_LOAD(A, base);
; #pragma unroll 2
;                 for (int j = 0; j < CH; j += 2) { const LAS float* sp = base + j * STEPF;
;                     SC_LOAD(B, sp + STEPF); SC_STEP(A);
;                     SC_LOAD(A, sp + 2 * STEPF);
;                     SC_STEP(B); }
	v_pk_mul_f32 v[78:79], v[2:3], v[132:133] op_sel_hi:[1,0]
	v_pk_mul_f32 v[92:93], v[2:3], v[46:47] op_sel_hi:[1,0]
	v_pk_fma_f32 v[78:79], v[4:5], v[132:133], v[78:79] op_sel:[0,1,0] op_sel_hi:[1,1,1]
	v_pk_fma_f32 v[92:93], v[4:5], v[46:47], v[92:93] op_sel:[0,1,0] op_sel_hi:[1,1,1]
	v_pk_fma_f32 v[78:79], v[6:7], v[134:135], v[78:79] op_sel_hi:[1,0,1]
	v_pk_fma_f32 v[92:93], v[6:7], v[48:49], v[92:93] op_sel_hi:[1,0,1]
	v_pk_fma_f32 v[78:79], v[8:9], v[134:135], v[78:79] op_sel:[0,1,0] op_sel_hi:[1,1,1]
	v_pk_mul_f32 v[82:83], v[74:75], v[140:141] op_sel_hi:[1,0]
	v_pk_fma_f32 v[92:93], v[8:9], v[48:49], v[92:93] op_sel:[0,1,0] op_sel_hi:[1,1,1]
	v_pk_mul_f32 v[84:85], v[74:75], v[140:141] op_sel:[0,1] op_sel_hi:[1,1]
	v_add_f32_dpp v78, v78, v78 quad_perm:[1,0,3,2] row_mask:0xf bank_mask:0xf bound_ctrl:1
	v_add_f32_dpp v79, v79, v79 quad_perm:[1,0,3,2] row_mask:0xf bank_mask:0xf bound_ctrl:1
	v_pk_mul_f32 v[86:87], v[74:75], v[142:143] op_sel_hi:[1,0]
	ds_read_b128 v[30:33], v100 offset:20480
	v_add_f32_dpp v78, v78, v78 quad_perm:[2,3,0,1] row_mask:0xf bank_mask:0xf bound_ctrl:1
	v_add_f32_dpp v79, v79, v79 quad_perm:[2,3,0,1] row_mask:0xf bank_mask:0xf bound_ctrl:1
	v_pk_mul_f32 v[88:89], v[74:75], v[142:143] op_sel:[0,1] op_sel_hi:[1,1]
	ds_read_b128 v[38:41], v100 offset:20992
	v_add_f32_dpp v78, v78, v78 row_half_mirror row_mask:0xf bank_mask:0xf bound_ctrl:1
	v_add_f32_dpp v79, v79, v79 row_half_mirror row_mask:0xf bank_mask:0xf bound_ctrl:1
	v_pk_fma_f32 v[82:83], v[2:3], v[136:137], v[82:83] op_sel_hi:[1,0,1]
	ds_read_b128 v[34:37], v100 offset:20736
	v_add_f32_dpp v78, v78, v78 row_mirror row_mask:0xf bank_mask:0xf bound_ctrl:1
	v_add_f32_dpp v79, v79, v79 row_mirror row_mask:0xf bank_mask:0xf bound_ctrl:1
	v_pk_fma_f32 v[84:85], v[4:5], v[136:137], v[84:85] op_sel:[0,1,0] op_sel_hi:[1,1,1]
	ds_read_b128 v[42:45], v100 offset:21248
	v_pk_fma_f32 v[86:87], v[6:7], v[138:139], v[86:87] op_sel_hi:[1,0,1]
	ds_read_b128 v[46:49], v100 offset:21504
	v_pk_fma_f32 v[88:89], v[8:9], v[138:139], v[88:89] op_sel:[0,1,0] op_sel_hi:[1,1,1]
	ds_read_b128 v[70:73], v101 offset:128
	v_cndmask_b32_e64 v116, v112, v114, s[52:53]
	v_cndmask_b32_e64 v118, v114, v112, s[52:53]
	v_cndmask_b32_e64 v117, v113, v115, s[52:53]
	v_pk_fma_f32 v[2:3], v[78:79], v[144:145], v[82:83] op_sel_hi:[1,0,1]
	v_pk_fma_f32 v[4:5], v[78:79], v[144:145], v[84:85] op_sel:[0,1,0] op_sel_hi:[1,1,1]
	v_pk_fma_f32 v[6:7], v[78:79], v[146:147], v[86:87] op_sel_hi:[1,0,1]
	v_pk_fma_f32 v[8:9], v[78:79], v[146:147], v[88:89] op_sel:[0,1,0] op_sel_hi:[1,1,1]
	v_cndmask_b32_e64 v119, v115, v113, s[52:53]
	v_add_f32_dpp v120, v118, v116 quad_perm:[2,3,0,1] row_mask:0xf bank_mask:0xf bound_ctrl:1
	s_nop 0
	v_add_f32_dpp v121, v119, v117 quad_perm:[2,3,0,1] row_mask:0xf bank_mask:0xf bound_ctrl:1
	s_waitcnt lgkmcnt(6)
	v_pk_mul_f32 v[78:79], v[2:3], v[10:11] op_sel_hi:[1,0]
	v_pk_mul_f32 v[94:95], v[2:3], v[148:149] op_sel_hi:[1,0]
	v_pk_fma_f32 v[78:79], v[4:5], v[10:11], v[78:79] op_sel:[0,1,0] op_sel_hi:[1,1,1]
	v_pk_fma_f32 v[94:95], v[4:5], v[148:149], v[94:95] op_sel:[0,1,0] op_sel_hi:[1,1,1]
	v_pk_fma_f32 v[78:79], v[6:7], v[12:13], v[78:79] op_sel_hi:[1,0,1]
	v_pk_fma_f32 v[94:95], v[6:7], v[150:151], v[94:95] op_sel_hi:[1,0,1]
	v_pk_fma_f32 v[78:79], v[8:9], v[12:13], v[78:79] op_sel:[0,1,0] op_sel_hi:[1,1,1]
	v_pk_mul_f32 v[82:83], v[76:77], v[18:19] op_sel_hi:[1,0]
	v_pk_fma_f32 v[94:95], v[8:9], v[150:151], v[94:95] op_sel:[0,1,0] op_sel_hi:[1,1,1]
	v_pk_mul_f32 v[84:85], v[76:77], v[18:19] op_sel:[0,1] op_sel_hi:[1,1]
	v_add_f32_dpp v78, v78, v78 quad_perm:[1,0,3,2] row_mask:0xf bank_mask:0xf bound_ctrl:1
	v_add_f32_dpp v79, v79, v79 quad_perm:[1,0,3,2] row_mask:0xf bank_mask:0xf bound_ctrl:1
	v_pk_mul_f32 v[86:87], v[76:77], v[20:21] op_sel_hi:[1,0]
	ds_read_b128 v[132:135], v100 offset:21760
	v_add_f32_dpp v78, v78, v78 quad_perm:[2,3,0,1] row_mask:0xf bank_mask:0xf bound_ctrl:1
	v_add_f32_dpp v79, v79, v79 quad_perm:[2,3,0,1] row_mask:0xf bank_mask:0xf bound_ctrl:1
	v_pk_mul_f32 v[88:89], v[76:77], v[20:21] op_sel:[0,1] op_sel_hi:[1,1]
	ds_read_b128 v[140:143], v100 offset:22272
	v_add_f32_dpp v78, v78, v78 row_half_mirror row_mask:0xf bank_mask:0xf bound_ctrl:1
	v_add_f32_dpp v79, v79, v79 row_half_mirror row_mask:0xf bank_mask:0xf bound_ctrl:1
	v_pk_fma_f32 v[82:83], v[2:3], v[14:15], v[82:83] op_sel_hi:[1,0,1]
	ds_read_b128 v[136:139], v100 offset:22016
	v_add_f32_dpp v78, v78, v78 row_mirror row_mask:0xf bank_mask:0xf bound_ctrl:1
	v_add_f32_dpp v79, v79, v79 row_mirror row_mask:0xf bank_mask:0xf bound_ctrl:1
	v_pk_fma_f32 v[84:85], v[4:5], v[14:15], v[84:85] op_sel:[0,1,0] op_sel_hi:[1,1,1]
	ds_read_b128 v[144:147], v100 offset:22528
	v_pk_fma_f32 v[86:87], v[6:7], v[16:17], v[86:87] op_sel_hi:[1,0,1]
	ds_read_b128 v[148:151], v100 offset:22784
	v_pk_fma_f32 v[88:89], v[8:9], v[16:17], v[88:89] op_sel:[0,1,0] op_sel_hi:[1,1,1]
	v_add_f32_dpp v120, v120, v120 row_ror:4 row_mask:0xf bank_mask:0xf bound_ctrl:1
	v_add_f32_dpp v121, v121, v121 row_ror:4 row_mask:0xf bank_mask:0xf bound_ctrl:1
	s_nop 0
	v_add_f32_dpp v120, v120, v120 row_ror:8 row_mask:0xf bank_mask:0xf bound_ctrl:1
	v_pk_fma_f32 v[2:3], v[78:79], v[22:23], v[82:83] op_sel_hi:[1,0,1]
	v_pk_fma_f32 v[4:5], v[78:79], v[22:23], v[84:85] op_sel:[0,1,0] op_sel_hi:[1,1,1]
	v_pk_fma_f32 v[6:7], v[78:79], v[24:25], v[86:87] op_sel_hi:[1,0,1]
	v_pk_fma_f32 v[8:9], v[78:79], v[24:25], v[88:89] op_sel:[0,1,0] op_sel_hi:[1,1,1]
	v_add_f32_dpp v121, v121, v121 row_ror:8 row_mask:0xf bank_mask:0xf bound_ctrl:1
	global_store_dwordx2 v102, v[120:121], s[10:11]
	v_add_u32_e32 v102, s13, v102
	s_waitcnt lgkmcnt(5)
; #define LAS __attribute__((address_space(3)))
; __device__ __forceinline__ void phase_scan(CParams& P, LAS unsigned char* lds) {
;     ...
;             f32x4 Ar0, Ar1, Aw0, Aw1, Ak0, Ak1, Aq0, Aq1, Ab0, Ab1, Br0, Br1, Bw0, Bw1, Bk0, Bk1, Bq0, Bq1, Bb0, Bb1; float Avv, Bvv;
; #pragma unroll 1
;             for (int c = 0; c < NCH; ++c) {
;                 __syncthreads();
;                 const LAS float* base = lf + (c & 1) * BUFF + 8 * oct;
;                 SC_LOAD(A, base);
; #pragma unroll 2
;                 for (int j = 0; j < CH; j += 2) { const LAS float* sp = base + j * STEPF;
;                     SC_LOAD(B, sp + STEPF); SC_STEP(A);
;                     SC_LOAD(A, sp + 2 * STEPF);
;                     SC_STEP(B); }
	v_pk_mul_f32 v[78:79], v[2:3], v[30:31] op_sel_hi:[1,0]
	v_pk_mul_f32 v[96:97], v[2:3], v[26:27] op_sel_hi:[1,0]
	v_pk_fma_f32 v[78:79], v[4:5], v[30:31], v[78:79] op_sel:[0,1,0] op_sel_hi:[1,1,1]
	v_pk_fma_f32 v[96:97], v[4:5], v[26:27], v[96:97] op_sel:[0,1,0] op_sel_hi:[1,1,1]
	v_pk_fma_f32 v[78:79], v[6:7], v[32:33], v[78:79] op_sel_hi:[1,0,1]
	v_pk_fma_f32 v[96:97], v[6:7], v[28:29], v[96:97] op_sel_hi:[1,0,1]
	v_pk_fma_f32 v[78:79], v[8:9], v[32:33], v[78:79] op_sel:[0,1,0] op_sel_hi:[1,1,1]
	v_pk_mul_f32 v[82:83], v[70:71], v[38:39] op_sel_hi:[1,0]
	v_pk_fma_f32 v[96:97], v[8:9], v[28:29], v[96:97] op_sel:[0,1,0] op_sel_hi:[1,1,1]
	v_pk_mul_f32 v[84:85], v[70:71], v[38:39] op_sel:[0,1] op_sel_hi:[1,1]
	v_add_f32_dpp v78, v78, v78 quad_perm:[1,0,3,2] row_mask:0xf bank_mask:0xf bound_ctrl:1
	v_add_f32_dpp v79, v79, v79 quad_perm:[1,0,3,2] row_mask:0xf bank_mask:0xf bound_ctrl:1
	v_pk_mul_f32 v[86:87], v[70:71], v[40:41] op_sel_hi:[1,0]
	ds_read_b128 v[10:13], v100 offset:23040
	v_add_f32_dpp v78, v78, v78 quad_perm:[2,3,0,1] row_mask:0xf bank_mask:0xf bound_ctrl:1
	v_add_f32_dpp v79, v79, v79 quad_perm:[2,3,0,1] row_mask:0xf bank_mask:0xf bound_ctrl:1
	v_pk_mul_f32 v[88:89], v[70:71], v[40:41] op_sel:[0,1] op_sel_hi:[1,1]
	ds_read_b128 v[18:21], v100 offset:23552
	v_add_f32_dpp v78, v78, v78 row_half_mirror row_mask:0xf bank_mask:0xf bound_ctrl:1
	v_add_f32_dpp v79, v79, v79 row_half_mirror row_mask:0xf bank_mask:0xf bound_ctrl:1
	v_pk_fma_f32 v[82:83], v[2:3], v[34:35], v[82:83] op_sel_hi:[1,0,1]
	ds_read_b128 v[14:17], v100 offset:23296
	v_add_f32_dpp v78, v78, v78 row_mirror row_mask:0xf bank_mask:0xf bound_ctrl:1
	v_add_f32_dpp v79, v79, v79 row_mirror row_mask:0xf bank_mask:0xf bound_ctrl:1
	v_pk_fma_f32 v[84:85], v[4:5], v[34:35], v[84:85] op_sel:[0,1,0] op_sel_hi:[1,1,1]
	ds_read_b128 v[22:25], v100 offset:23808
	v_pk_fma_f32 v[86:87], v[6:7], v[36:37], v[86:87] op_sel_hi:[1,0,1]
	ds_read_b128 v[26:29], v100 offset:24064
	v_pk_fma_f32 v[88:89], v[8:9], v[36:37], v[88:89] op_sel:[0,1,0] op_sel_hi:[1,1,1]
	ds_read_b128 v[74:77], v101 offset:144
	v_cndmask_b32_e64 v104, v90, v92, s[50:51]
	v_cndmask_b32_e64 v106, v92, v90, s[50:51]
	v_cndmask_b32_e64 v108, v94, v96, s[50:51]
	v_pk_fma_f32 v[2:3], v[78:79], v[42:43], v[82:83] op_sel_hi:[1,0,1]
	v_pk_fma_f32 v[4:5], v[78:79], v[42:43], v[84:85] op_sel:[0,1,0] op_sel_hi:[1,1,1]
	v_pk_fma_f32 v[6:7], v[78:79], v[44:45], v[86:87] op_sel_hi:[1,0,1]
	v_pk_fma_f32 v[8:9], v[78:79], v[44:45], v[88:89] op_sel:[0,1,0] op_sel_hi:[1,1,1]
	v_cndmask_b32_e64 v110, v96, v94, s[50:51]
	v_cndmask_b32_e64 v105, v91, v93, s[50:51]
	v_cndmask_b32_e64 v107, v93, v91, s[50:51]
	s_waitcnt lgkmcnt(6)
	v_pk_mul_f32 v[78:79], v[2:3], v[132:133] op_sel_hi:[1,0]
	v_pk_mul_f32 v[90:91], v[2:3], v[46:47] op_sel_hi:[1,0]
	v_pk_fma_f32 v[78:79], v[4:5], v[132:133], v[78:79] op_sel:[0,1,0] op_sel_hi:[1,1,1]
	v_pk_fma_f32 v[90:91], v[4:5], v[46:47], v[90:91] op_sel:[0,1,0] op_sel_hi:[1,1,1]
	v_pk_fma_f32 v[78:79], v[6:7], v[134:135], v[78:79] op_sel_hi:[1,0,1]
	v_pk_fma_f32 v[90:91], v[6:7], v[48:49], v[90:91] op_sel_hi:[1,0,1]
	v_pk_fma_f32 v[78:79], v[8:9], v[134:135], v[78:79] op_sel:[0,1,0] op_sel_hi:[1,1,1]
	v_pk_mul_f32 v[82:83], v[72:73], v[140:141] op_sel_hi:[1,0]
	v_pk_fma_f32 v[90:91], v[8:9], v[48:49], v[90:91] op_sel:[0,1,0] op_sel_hi:[1,1,1]
	v_pk_mul_f32 v[84:85], v[72:73], v[140:141] op_sel:[0,1] op_sel_hi:[1,1]
	v_add_f32_dpp v78, v78, v78 quad_perm:[1,0,3,2] row_mask:0xf bank_mask:0xf bound_ctrl:1
	v_add_f32_dpp v79, v79, v79 quad_perm:[1,0,3,2] row_mask:0xf bank_mask:0xf bound_ctrl:1
	v_pk_mul_f32 v[86:87], v[72:73], v[142:143] op_sel_hi:[1,0]
	ds_read_b128 v[30:33], v100 offset:24320
	v_add_f32_dpp v78, v78, v78 quad_perm:[2,3,0,1] row_mask:0xf bank_mask:0xf bound_ctrl:1
	v_add_f32_dpp v79, v79, v79 quad_perm:[2,3,0,1] row_mask:0xf bank_mask:0xf bound_ctrl:1
	v_pk_mul_f32 v[88:89], v[72:73], v[142:143] op_sel:[0,1] op_sel_hi:[1,1]
	ds_read_b128 v[38:41], v100 offset:24832
	v_add_f32_dpp v78, v78, v78 row_half_mirror row_mask:0xf bank_mask:0xf bound_ctrl:1
	v_add_f32_dpp v79, v79, v79 row_half_mirror row_mask:0xf bank_mask:0xf bound_ctrl:1
	v_pk_fma_f32 v[82:83], v[2:3], v[136:137], v[82:83] op_sel_hi:[1,0,1]
	ds_read_b128 v[34:37], v100 offset:24576
	v_add_f32_dpp v78, v78, v78 row_mirror row_mask:0xf bank_mask:0xf bound_ctrl:1
	v_add_f32_dpp v79, v79, v79 row_mirror row_mask:0xf bank_mask:0xf bound_ctrl:1
	v_pk_fma_f32 v[84:85], v[4:5], v[136:137], v[84:85] op_sel:[0,1,0] op_sel_hi:[1,1,1]
	ds_read_b128 v[42:45], v100 offset:25088
	v_pk_fma_f32 v[86:87], v[6:7], v[138:139], v[86:87] op_sel_hi:[1,0,1]
	ds_read_b128 v[46:49], v100 offset:25344
	v_pk_fma_f32 v[88:89], v[8:9], v[138:139], v[88:89] op_sel:[0,1,0] op_sel_hi:[1,1,1]
	v_cndmask_b32_e64 v109, v95, v97, s[50:51]
	v_cndmask_b32_e64 v111, v97, v95, s[50:51]
	v_add_f32_dpp v112, v106, v104 quad_perm:[1,0,3,2] row_mask:0xf bank_mask:0xf bound_ctrl:1
	v_pk_fma_f32 v[2:3], v[78:79], v[144:145], v[82:83] op_sel_hi:[1,0,1]
	v_pk_fma_f32 v[4:5], v[78:79], v[144:145], v[84:85] op_sel:[0,1,0] op_sel_hi:[1,1,1]
	v_pk_fma_f32 v[6:7], v[78:79], v[146:147], v[86:87] op_sel_hi:[1,0,1]
	v_pk_fma_f32 v[8:9], v[78:79], v[146:147], v[88:89] op_sel:[0,1,0] op_sel_hi:[1,1,1]
	v_add_f32_dpp v114, v110, v108 quad_perm:[1,0,3,2] row_mask:0xf bank_mask:0xf bound_ctrl:1
	v_add_f32_dpp v113, v107, v105 quad_perm:[1,0,3,2] row_mask:0xf bank_mask:0xf bound_ctrl:1
	v_add_f32_dpp v115, v111, v109 quad_perm:[1,0,3,2] row_mask:0xf bank_mask:0xf bound_ctrl:1
	s_waitcnt lgkmcnt(5)
; #define LAS __attribute__((address_space(3)))
; __device__ __forceinline__ void phase_scan(CParams& P, LAS unsigned char* lds) {
;     ...
;             f32x4 Ar0, Ar1, Aw0, Aw1, Ak0, Ak1, Aq0, Aq1, Ab0, Ab1, Br0, Br1, Bw0, Bw1, Bk0, Bk1, Bq0, Bq1, Bb0, Bb1; float Avv, Bvv;
; #pragma unroll 1
;             for (int c = 0; c < NCH; ++c) {
;                 __syncthreads();
;                 const LAS float* base = lf + (c & 1) * BUFF + 8 * oct;
;                 SC_LOAD(A, base);
; #pragma unroll 2
;                 for (int j = 0; j < CH; j += 2) { const LAS float* sp = base + j * STEPF;
;                     SC_LOAD(B, sp + STEPF); SC_STEP(A);
;                     SC_LOAD(A, sp + 2 * STEPF);
;                     SC_STEP(B); }
	v_pk_mul_f32 v[78:79], v[2:3], v[10:11] op_sel_hi:[1,0]
	v_pk_mul_f32 v[92:93], v[2:3], v[148:149] op_sel_hi:[1,0]
	v_pk_fma_f32 v[78:79], v[4:5], v[10:11], v[78:79] op_sel:[0,1,0] op_sel_hi:[1,1,1]
	v_pk_fma_f32 v[92:93], v[4:5], v[148:149], v[92:93] op_sel:[0,1,0] op_sel_hi:[1,1,1]
	v_pk_fma_f32 v[78:79], v[6:7], v[12:13], v[78:79] op_sel_hi:[1,0,1]
	v_pk_fma_f32 v[92:93], v[6:7], v[150:151], v[92:93] op_sel_hi:[1,0,1]
	v_pk_fma_f32 v[78:79], v[8:9], v[12:13], v[78:79] op_sel:[0,1,0] op_sel_hi:[1,1,1]
	v_pk_mul_f32 v[82:83], v[74:75], v[18:19] op_sel_hi:[1,0]
	v_pk_fma_f32 v[92:93], v[8:9], v[150:151], v[92:93] op_sel:[0,1,0] op_sel_hi:[1,1,1]
	v_pk_mul_f32 v[84:85], v[74:75], v[18:19] op_sel:[0,1] op_sel_hi:[1,1]
	v_add_f32_dpp v78, v78, v78 quad_perm:[1,0,3,2] row_mask:0xf bank_mask:0xf bound_ctrl:1
	v_add_f32_dpp v79, v79, v79 quad_perm:[1,0,3,2] row_mask:0xf bank_mask:0xf bound_ctrl:1
	v_pk_mul_f32 v[86:87], v[74:75], v[20:21] op_sel_hi:[1,0]
	ds_read_b128 v[132:135], v100 offset:25600
	v_add_f32_dpp v78, v78, v78 quad_perm:[2,3,0,1] row_mask:0xf bank_mask:0xf bound_ctrl:1
	v_add_f32_dpp v79, v79, v79 quad_perm:[2,3,0,1] row_mask:0xf bank_mask:0xf bound_ctrl:1
	v_pk_mul_f32 v[88:89], v[74:75], v[20:21] op_sel:[0,1] op_sel_hi:[1,1]
	ds_read_b128 v[140:143], v100 offset:26112
	v_add_f32_dpp v78, v78, v78 row_half_mirror row_mask:0xf bank_mask:0xf bound_ctrl:1
	v_add_f32_dpp v79, v79, v79 row_half_mirror row_mask:0xf bank_mask:0xf bound_ctrl:1
	v_pk_fma_f32 v[82:83], v[2:3], v[14:15], v[82:83] op_sel_hi:[1,0,1]
	ds_read_b128 v[136:139], v100 offset:25856
	v_add_f32_dpp v78, v78, v78 row_mirror row_mask:0xf bank_mask:0xf bound_ctrl:1
	v_add_f32_dpp v79, v79, v79 row_mirror row_mask:0xf bank_mask:0xf bound_ctrl:1
	v_pk_fma_f32 v[84:85], v[4:5], v[14:15], v[84:85] op_sel:[0,1,0] op_sel_hi:[1,1,1]
	ds_read_b128 v[144:147], v100 offset:26368
	v_pk_fma_f32 v[86:87], v[6:7], v[16:17], v[86:87] op_sel_hi:[1,0,1]
	ds_read_b128 v[148:151], v100 offset:26624
	v_pk_fma_f32 v[88:89], v[8:9], v[16:17], v[88:89] op_sel:[0,1,0] op_sel_hi:[1,1,1]
	ds_read_b128 v[70:73], v101 offset:160
	v_cndmask_b32_e64 v116, v112, v114, s[52:53]
	v_cndmask_b32_e64 v118, v114, v112, s[52:53]
	v_cndmask_b32_e64 v117, v113, v115, s[52:53]
	v_pk_fma_f32 v[2:3], v[78:79], v[22:23], v[82:83] op_sel_hi:[1,0,1]
	v_pk_fma_f32 v[4:5], v[78:79], v[22:23], v[84:85] op_sel:[0,1,0] op_sel_hi:[1,1,1]
	v_pk_fma_f32 v[6:7], v[78:79], v[24:25], v[86:87] op_sel_hi:[1,0,1]
	v_pk_fma_f32 v[8:9], v[78:79], v[24:25], v[88:89] op_sel:[0,1,0] op_sel_hi:[1,1,1]
	v_cndmask_b32_e64 v119, v115, v113, s[52:53]
	v_add_f32_dpp v120, v118, v116 quad_perm:[2,3,0,1] row_mask:0xf bank_mask:0xf bound_ctrl:1
	s_nop 0
	v_add_f32_dpp v121, v119, v117 quad_perm:[2,3,0,1] row_mask:0xf bank_mask:0xf bound_ctrl:1
	s_waitcnt lgkmcnt(6)
	v_pk_mul_f32 v[78:79], v[2:3], v[30:31] op_sel_hi:[1,0]
	v_pk_mul_f32 v[94:95], v[2:3], v[26:27] op_sel_hi:[1,0]
	v_pk_fma_f32 v[78:79], v[4:5], v[30:31], v[78:79] op_sel:[0,1,0] op_sel_hi:[1,1,1]
	v_pk_fma_f32 v[94:95], v[4:5], v[26:27], v[94:95] op_sel:[0,1,0] op_sel_hi:[1,1,1]
	v_pk_fma_f32 v[78:79], v[6:7], v[32:33], v[78:79] op_sel_hi:[1,0,1]
	v_pk_fma_f32 v[94:95], v[6:7], v[28:29], v[94:95] op_sel_hi:[1,0,1]
	v_pk_fma_f32 v[78:79], v[8:9], v[32:33], v[78:79] op_sel:[0,1,0] op_sel_hi:[1,1,1]
	v_pk_mul_f32 v[82:83], v[76:77], v[38:39] op_sel_hi:[1,0]
	v_pk_fma_f32 v[94:95], v[8:9], v[28:29], v[94:95] op_sel:[0,1,0] op_sel_hi:[1,1,1]
	v_pk_mul_f32 v[84:85], v[76:77], v[38:39] op_sel:[0,1] op_sel_hi:[1,1]
	v_add_f32_dpp v78, v78, v78 quad_perm:[1,0,3,2] row_mask:0xf bank_mask:0xf bound_ctrl:1
	v_add_f32_dpp v79, v79, v79 quad_perm:[1,0,3,2] row_mask:0xf bank_mask:0xf bound_ctrl:1
	v_pk_mul_f32 v[86:87], v[76:77], v[40:41] op_sel_hi:[1,0]
	ds_read_b128 v[10:13], v100 offset:26880
	v_add_f32_dpp v78, v78, v78 quad_perm:[2,3,0,1] row_mask:0xf bank_mask:0xf bound_ctrl:1
	v_add_f32_dpp v79, v79, v79 quad_perm:[2,3,0,1] row_mask:0xf bank_mask:0xf bound_ctrl:1
	v_pk_mul_f32 v[88:89], v[76:77], v[40:41] op_sel:[0,1] op_sel_hi:[1,1]
	ds_read_b128 v[18:21], v100 offset:27392
	v_add_f32_dpp v78, v78, v78 row_half_mirror row_mask:0xf bank_mask:0xf bound_ctrl:1
	v_add_f32_dpp v79, v79, v79 row_half_mirror row_mask:0xf bank_mask:0xf bound_ctrl:1
	v_pk_fma_f32 v[82:83], v[2:3], v[34:35], v[82:83] op_sel_hi:[1,0,1]
	ds_read_b128 v[14:17], v100 offset:27136
	v_add_f32_dpp v78, v78, v78 row_mirror row_mask:0xf bank_mask:0xf bound_ctrl:1
	v_add_f32_dpp v79, v79, v79 row_mirror row_mask:0xf bank_mask:0xf bound_ctrl:1
	v_pk_fma_f32 v[84:85], v[4:5], v[34:35], v[84:85] op_sel:[0,1,0] op_sel_hi:[1,1,1]
	ds_read_b128 v[22:25], v100 offset:27648
	v_pk_fma_f32 v[86:87], v[6:7], v[36:37], v[86:87] op_sel_hi:[1,0,1]
	ds_read_b128 v[26:29], v100 offset:27904
	v_pk_fma_f32 v[88:89], v[8:9], v[36:37], v[88:89] op_sel:[0,1,0] op_sel_hi:[1,1,1]
	v_add_f32_dpp v120, v120, v120 row_ror:4 row_mask:0xf bank_mask:0xf bound_ctrl:1
	v_add_f32_dpp v121, v121, v121 row_ror:4 row_mask:0xf bank_mask:0xf bound_ctrl:1
	s_nop 0
	v_add_f32_dpp v120, v120, v120 row_ror:8 row_mask:0xf bank_mask:0xf bound_ctrl:1
	v_pk_fma_f32 v[2:3], v[78:79], v[42:43], v[82:83] op_sel_hi:[1,0,1]
	v_pk_fma_f32 v[4:5], v[78:79], v[42:43], v[84:85] op_sel:[0,1,0] op_sel_hi:[1,1,1]
	v_pk_fma_f32 v[6:7], v[78:79], v[44:45], v[86:87] op_sel_hi:[1,0,1]
	v_pk_fma_f32 v[8:9], v[78:79], v[44:45], v[88:89] op_sel:[0,1,0] op_sel_hi:[1,1,1]
	v_add_f32_dpp v121, v121, v121 row_ror:8 row_mask:0xf bank_mask:0xf bound_ctrl:1
	global_store_dwordx2 v102, v[120:121], s[10:11]
	v_add_u32_e32 v102, s13, v102
	s_waitcnt lgkmcnt(5)
; #define LAS __attribute__((address_space(3)))
; __device__ __forceinline__ void phase_scan(CParams& P, LAS unsigned char* lds) {
;     ...
;             f32x4 Ar0, Ar1, Aw0, Aw1, Ak0, Ak1, Aq0, Aq1, Ab0, Ab1, Br0, Br1, Bw0, Bw1, Bk0, Bk1, Bq0, Bq1, Bb0, Bb1; float Avv, Bvv;
; #pragma unroll 1
;             for (int c = 0; c < NCH; ++c) {
;                 __syncthreads();
;                 const LAS float* base = lf + (c & 1) * BUFF + 8 * oct;
;                 SC_LOAD(A, base);
; #pragma unroll 2
;                 for (int j = 0; j < CH; j += 2) { const LAS float* sp = base + j * STEPF;
;                     SC_LOAD(B, sp + STEPF); SC_STEP(A);
;                     SC_LOAD(A, sp + 2 * STEPF);
;                     SC_STEP(B); }
	v_pk_mul_f32 v[78:79], v[2:3], v[132:133] op_sel_hi:[1,0]
	v_pk_mul_f32 v[96:97], v[2:3], v[46:47] op_sel_hi:[1,0]
	v_pk_fma_f32 v[78:79], v[4:5], v[132:133], v[78:79] op_sel:[0,1,0] op_sel_hi:[1,1,1]
	v_pk_fma_f32 v[96:97], v[4:5], v[46:47], v[96:97] op_sel:[0,1,0] op_sel_hi:[1,1,1]
	v_pk_fma_f32 v[78:79], v[6:7], v[134:135], v[78:79] op_sel_hi:[1,0,1]
	v_pk_fma_f32 v[96:97], v[6:7], v[48:49], v[96:97] op_sel_hi:[1,0,1]
	v_pk_fma_f32 v[78:79], v[8:9], v[134:135], v[78:79] op_sel:[0,1,0] op_sel_hi:[1,1,1]
	v_pk_mul_f32 v[82:83], v[70:71], v[140:141] op_sel_hi:[1,0]
	v_pk_fma_f32 v[96:97], v[8:9], v[48:49], v[96:97] op_sel:[0,1,0] op_sel_hi:[1,1,1]
	v_pk_mul_f32 v[84:85], v[70:71], v[140:141] op_sel:[0,1] op_sel_hi:[1,1]
	v_add_f32_dpp v78, v78, v78 quad_perm:[1,0,3,2] row_mask:0xf bank_mask:0xf bound_ctrl:1
	v_add_f32_dpp v79, v79, v79 quad_perm:[1,0,3,2] row_mask:0xf bank_mask:0xf bound_ctrl:1
	v_pk_mul_f32 v[86:87], v[70:71], v[142:143] op_sel_hi:[1,0]
	ds_read_b128 v[30:33], v100 offset:28160
	v_add_f32_dpp v78, v78, v78 quad_perm:[2,3,0,1] row_mask:0xf bank_mask:0xf bound_ctrl:1
	v_add_f32_dpp v79, v79, v79 quad_perm:[2,3,0,1] row_mask:0xf bank_mask:0xf bound_ctrl:1
	v_pk_mul_f32 v[88:89], v[70:71], v[142:143] op_sel:[0,1] op_sel_hi:[1,1]
	ds_read_b128 v[38:41], v100 offset:28672
	v_add_f32_dpp v78, v78, v78 row_half_mirror row_mask:0xf bank_mask:0xf bound_ctrl:1
	v_add_f32_dpp v79, v79, v79 row_half_mirror row_mask:0xf bank_mask:0xf bound_ctrl:1
	v_pk_fma_f32 v[82:83], v[2:3], v[136:137], v[82:83] op_sel_hi:[1,0,1]
	ds_read_b128 v[34:37], v100 offset:28416
	v_add_f32_dpp v78, v78, v78 row_mirror row_mask:0xf bank_mask:0xf bound_ctrl:1
	v_add_f32_dpp v79, v79, v79 row_mirror row_mask:0xf bank_mask:0xf bound_ctrl:1
	v_pk_fma_f32 v[84:85], v[4:5], v[136:137], v[84:85] op_sel:[0,1,0] op_sel_hi:[1,1,1]
	ds_read_b128 v[42:45], v100 offset:28928
	v_pk_fma_f32 v[86:87], v[6:7], v[138:139], v[86:87] op_sel_hi:[1,0,1]
	ds_read_b128 v[46:49], v100 offset:29184
	v_pk_fma_f32 v[88:89], v[8:9], v[138:139], v[88:89] op_sel:[0,1,0] op_sel_hi:[1,1,1]
	ds_read_b128 v[74:77], v101 offset:176
	v_cndmask_b32_e64 v104, v90, v92, s[50:51]
	v_cndmask_b32_e64 v106, v92, v90, s[50:51]
	v_cndmask_b32_e64 v108, v94, v96, s[50:51]
	v_pk_fma_f32 v[2:3], v[78:79], v[144:145], v[82:83] op_sel_hi:[1,0,1]
	v_pk_fma_f32 v[4:5], v[78:79], v[144:145], v[84:85] op_sel:[0,1,0] op_sel_hi:[1,1,1]
	v_pk_fma_f32 v[6:7], v[78:79], v[146:147], v[86:87] op_sel_hi:[1,0,1]
	v_pk_fma_f32 v[8:9], v[78:79], v[146:147], v[88:89] op_sel:[0,1,0] op_sel_hi:[1,1,1]
	v_cndmask_b32_e64 v110, v96, v94, s[50:51]
	v_cndmask_b32_e64 v105, v91, v93, s[50:51]
	v_cndmask_b32_e64 v107, v93, v91, s[50:51]
	s_waitcnt lgkmcnt(6)
	v_pk_mul_f32 v[78:79], v[2:3], v[10:11] op_sel_hi:[1,0]
	v_pk_mul_f32 v[90:91], v[2:3], v[148:149] op_sel_hi:[1,0]
	v_pk_fma_f32 v[78:79], v[4:5], v[10:11], v[78:79] op_sel:[0,1,0] op_sel_hi:[1,1,1]
	v_pk_fma_f32 v[90:91], v[4:5], v[148:149], v[90:91] op_sel:[0,1,0] op_sel_hi:[1,1,1]
	v_pk_fma_f32 v[78:79], v[6:7], v[12:13], v[78:79] op_sel_hi:[1,0,1]
	v_pk_fma_f32 v[90:91], v[6:7], v[150:151], v[90:91] op_sel_hi:[1,0,1]
	v_pk_fma_f32 v[78:79], v[8:9], v[12:13], v[78:79] op_sel:[0,1,0] op_sel_hi:[1,1,1]
	v_pk_mul_f32 v[82:83], v[72:73], v[18:19] op_sel_hi:[1,0]
	v_pk_fma_f32 v[90:91], v[8:9], v[150:151], v[90:91] op_sel:[0,1,0] op_sel_hi:[1,1,1]
	v_pk_mul_f32 v[84:85], v[72:73], v[18:19] op_sel:[0,1] op_sel_hi:[1,1]
	v_add_f32_dpp v78, v78, v78 quad_perm:[1,0,3,2] row_mask:0xf bank_mask:0xf bound_ctrl:1
	v_add_f32_dpp v79, v79, v79 quad_perm:[1,0,3,2] row_mask:0xf bank_mask:0xf bound_ctrl:1
	v_pk_mul_f32 v[86:87], v[72:73], v[20:21] op_sel_hi:[1,0]
	ds_read_b128 v[132:135], v100 offset:29440
	v_add_f32_dpp v78, v78, v78 quad_perm:[2,3,0,1] row_mask:0xf bank_mask:0xf bound_ctrl:1
	v_add_f32_dpp v79, v79, v79 quad_perm:[2,3,0,1] row_mask:0xf bank_mask:0xf bound_ctrl:1
	v_pk_mul_f32 v[88:89], v[72:73], v[20:21] op_sel:[0,1] op_sel_hi:[1,1]
	ds_read_b128 v[140:143], v100 offset:29952
	v_add_f32_dpp v78, v78, v78 row_half_mirror row_mask:0xf bank_mask:0xf bound_ctrl:1
	v_add_f32_dpp v79, v79, v79 row_half_mirror row_mask:0xf bank_mask:0xf bound_ctrl:1
	v_pk_fma_f32 v[82:83], v[2:3], v[14:15], v[82:83] op_sel_hi:[1,0,1]
	ds_read_b128 v[136:139], v100 offset:29696
	v_add_f32_dpp v78, v78, v78 row_mirror row_mask:0xf bank_mask:0xf bound_ctrl:1
	v_add_f32_dpp v79, v79, v79 row_mirror row_mask:0xf bank_mask:0xf bound_ctrl:1
	v_pk_fma_f32 v[84:85], v[4:5], v[14:15], v[84:85] op_sel:[0,1,0] op_sel_hi:[1,1,1]
	ds_read_b128 v[144:147], v100 offset:30208
	v_pk_fma_f32 v[86:87], v[6:7], v[16:17], v[86:87] op_sel_hi:[1,0,1]
	ds_read_b128 v[148:151], v100 offset:30464
	v_pk_fma_f32 v[88:89], v[8:9], v[16:17], v[88:89] op_sel:[0,1,0] op_sel_hi:[1,1,1]
	v_cndmask_b32_e64 v109, v95, v97, s[50:51]
	v_cndmask_b32_e64 v111, v97, v95, s[50:51]
	v_add_f32_dpp v112, v106, v104 quad_perm:[1,0,3,2] row_mask:0xf bank_mask:0xf bound_ctrl:1
	v_pk_fma_f32 v[2:3], v[78:79], v[22:23], v[82:83] op_sel_hi:[1,0,1]
	v_pk_fma_f32 v[4:5], v[78:79], v[22:23], v[84:85] op_sel:[0,1,0] op_sel_hi:[1,1,1]
	v_pk_fma_f32 v[6:7], v[78:79], v[24:25], v[86:87] op_sel_hi:[1,0,1]
	v_pk_fma_f32 v[8:9], v[78:79], v[24:25], v[88:89] op_sel:[0,1,0] op_sel_hi:[1,1,1]
	v_add_f32_dpp v114, v110, v108 quad_perm:[1,0,3,2] row_mask:0xf bank_mask:0xf bound_ctrl:1
	v_add_f32_dpp v113, v107, v105 quad_perm:[1,0,3,2] row_mask:0xf bank_mask:0xf bound_ctrl:1
	v_add_f32_dpp v115, v111, v109 quad_perm:[1,0,3,2] row_mask:0xf bank_mask:0xf bound_ctrl:1
	s_waitcnt lgkmcnt(5)
; #define LAS __attribute__((address_space(3)))
; __device__ __forceinline__ void phase_scan(CParams& P, LAS unsigned char* lds) {
;     ...
; #pragma unroll 2
;                 for (int j = 0; j < CH; j += 2) { const LAS float* sp = base + j * STEPF;
;                     SC_LOAD(B, sp + STEPF); SC_STEP(A);
;                     SC_LOAD(A, sp + 2 * STEPF);
;                     SC_STEP(B); }
	v_pk_mul_f32 v[78:79], v[2:3], v[30:31] op_sel_hi:[1,0]
	v_pk_mul_f32 v[92:93], v[2:3], v[26:27] op_sel_hi:[1,0]
	v_pk_fma_f32 v[78:79], v[4:5], v[30:31], v[78:79] op_sel:[0,1,0] op_sel_hi:[1,1,1]
	v_pk_fma_f32 v[92:93], v[4:5], v[26:27], v[92:93] op_sel:[0,1,0] op_sel_hi:[1,1,1]
	v_pk_fma_f32 v[78:79], v[6:7], v[32:33], v[78:79] op_sel_hi:[1,0,1]
	v_pk_fma_f32 v[92:93], v[6:7], v[28:29], v[92:93] op_sel_hi:[1,0,1]
	v_pk_fma_f32 v[78:79], v[8:9], v[32:33], v[78:79] op_sel:[0,1,0] op_sel_hi:[1,1,1]
	v_pk_mul_f32 v[82:83], v[74:75], v[38:39] op_sel_hi:[1,0]
	v_pk_fma_f32 v[92:93], v[8:9], v[28:29], v[92:93] op_sel:[0,1,0] op_sel_hi:[1,1,1]
	v_pk_mul_f32 v[84:85], v[74:75], v[38:39] op_sel:[0,1] op_sel_hi:[1,1]
	v_add_f32_dpp v78, v78, v78 quad_perm:[1,0,3,2] row_mask:0xf bank_mask:0xf bound_ctrl:1
	v_add_f32_dpp v79, v79, v79 quad_perm:[1,0,3,2] row_mask:0xf bank_mask:0xf bound_ctrl:1
	v_pk_mul_f32 v[86:87], v[74:75], v[40:41] op_sel_hi:[1,0]
	ds_read_b128 v[10:13], v100 offset:30720
	v_add_f32_dpp v78, v78, v78 quad_perm:[2,3,0,1] row_mask:0xf bank_mask:0xf bound_ctrl:1
	v_add_f32_dpp v79, v79, v79 quad_perm:[2,3,0,1] row_mask:0xf bank_mask:0xf bound_ctrl:1
	v_pk_mul_f32 v[88:89], v[74:75], v[40:41] op_sel:[0,1] op_sel_hi:[1,1]
	ds_read_b128 v[18:21], v100 offset:31232
	v_add_f32_dpp v78, v78, v78 row_half_mirror row_mask:0xf bank_mask:0xf bound_ctrl:1
	v_add_f32_dpp v79, v79, v79 row_half_mirror row_mask:0xf bank_mask:0xf bound_ctrl:1
	v_pk_fma_f32 v[82:83], v[2:3], v[34:35], v[82:83] op_sel_hi:[1,0,1]
	ds_read_b128 v[14:17], v100 offset:30976
	v_add_f32_dpp v78, v78, v78 row_mirror row_mask:0xf bank_mask:0xf bound_ctrl:1
	v_add_f32_dpp v79, v79, v79 row_mirror row_mask:0xf bank_mask:0xf bound_ctrl:1
	v_pk_fma_f32 v[84:85], v[4:5], v[34:35], v[84:85] op_sel:[0,1,0] op_sel_hi:[1,1,1]
	ds_read_b128 v[22:25], v100 offset:31488
	v_pk_fma_f32 v[86:87], v[6:7], v[36:37], v[86:87] op_sel_hi:[1,0,1]
	ds_read_b128 v[26:29], v100 offset:31744
	v_pk_fma_f32 v[88:89], v[8:9], v[36:37], v[88:89] op_sel:[0,1,0] op_sel_hi:[1,1,1]
	ds_read_b128 v[70:73], v101 offset:192
	v_cndmask_b32_e64 v116, v112, v114, s[52:53]
	v_cndmask_b32_e64 v118, v114, v112, s[52:53]
	v_cndmask_b32_e64 v117, v113, v115, s[52:53]
	v_pk_fma_f32 v[2:3], v[78:79], v[42:43], v[82:83] op_sel_hi:[1,0,1]
	v_pk_fma_f32 v[4:5], v[78:79], v[42:43], v[84:85] op_sel:[0,1,0] op_sel_hi:[1,1,1]
	v_pk_fma_f32 v[6:7], v[78:79], v[44:45], v[86:87] op_sel_hi:[1,0,1]
	v_pk_fma_f32 v[8:9], v[78:79], v[44:45], v[88:89] op_sel:[0,1,0] op_sel_hi:[1,1,1]
	v_cndmask_b32_e64 v119, v115, v113, s[52:53]
	v_add_f32_dpp v120, v118, v116 quad_perm:[2,3,0,1] row_mask:0xf bank_mask:0xf bound_ctrl:1
	s_nop 0
	v_add_f32_dpp v121, v119, v117 quad_perm:[2,3,0,1] row_mask:0xf bank_mask:0xf bound_ctrl:1
	s_waitcnt lgkmcnt(6)
	v_pk_mul_f32 v[78:79], v[2:3], v[132:133] op_sel_hi:[1,0]
	v_pk_mul_f32 v[94:95], v[2:3], v[46:47] op_sel_hi:[1,0]
	v_pk_fma_f32 v[78:79], v[4:5], v[132:133], v[78:79] op_sel:[0,1,0] op_sel_hi:[1,1,1]
	v_pk_fma_f32 v[94:95], v[4:5], v[46:47], v[94:95] op_sel:[0,1,0] op_sel_hi:[1,1,1]
	v_pk_fma_f32 v[78:79], v[6:7], v[134:135], v[78:79] op_sel_hi:[1,0,1]
	v_pk_fma_f32 v[94:95], v[6:7], v[48:49], v[94:95] op_sel_hi:[1,0,1]
	v_pk_fma_f32 v[78:79], v[8:9], v[134:135], v[78:79] op_sel:[0,1,0] op_sel_hi:[1,1,1]
	v_pk_mul_f32 v[82:83], v[76:77], v[140:141] op_sel_hi:[1,0]
	v_pk_fma_f32 v[94:95], v[8:9], v[48:49], v[94:95] op_sel:[0,1,0] op_sel_hi:[1,1,1]
	v_pk_mul_f32 v[84:85], v[76:77], v[140:141] op_sel:[0,1] op_sel_hi:[1,1]
	v_add_f32_dpp v78, v78, v78 quad_perm:[1,0,3,2] row_mask:0xf bank_mask:0xf bound_ctrl:1
	v_add_f32_dpp v79, v79, v79 quad_perm:[1,0,3,2] row_mask:0xf bank_mask:0xf bound_ctrl:1
	v_pk_mul_f32 v[86:87], v[76:77], v[142:143] op_sel_hi:[1,0]
	ds_read_b128 v[30:33], v100 offset:32000
	v_add_f32_dpp v78, v78, v78 quad_perm:[2,3,0,1] row_mask:0xf bank_mask:0xf bound_ctrl:1
	v_add_f32_dpp v79, v79, v79 quad_perm:[2,3,0,1] row_mask:0xf bank_mask:0xf bound_ctrl:1
	v_pk_mul_f32 v[88:89], v[76:77], v[142:143] op_sel:[0,1] op_sel_hi:[1,1]
	ds_read_b128 v[38:41], v100 offset:32512
	v_add_f32_dpp v78, v78, v78 row_half_mirror row_mask:0xf bank_mask:0xf bound_ctrl:1
	v_add_f32_dpp v79, v79, v79 row_half_mirror row_mask:0xf bank_mask:0xf bound_ctrl:1
	v_pk_fma_f32 v[82:83], v[2:3], v[136:137], v[82:83] op_sel_hi:[1,0,1]
	ds_read_b128 v[34:37], v100 offset:32256
	v_add_f32_dpp v78, v78, v78 row_mirror row_mask:0xf bank_mask:0xf bound_ctrl:1
	v_add_f32_dpp v79, v79, v79 row_mirror row_mask:0xf bank_mask:0xf bound_ctrl:1
	v_pk_fma_f32 v[84:85], v[4:5], v[136:137], v[84:85] op_sel:[0,1,0] op_sel_hi:[1,1,1]
	ds_read_b128 v[42:45], v100 offset:32768
	v_pk_fma_f32 v[86:87], v[6:7], v[138:139], v[86:87] op_sel_hi:[1,0,1]
	ds_read_b128 v[46:49], v100 offset:33024
	v_pk_fma_f32 v[88:89], v[8:9], v[138:139], v[88:89] op_sel:[0,1,0] op_sel_hi:[1,1,1]
	v_add_f32_dpp v120, v120, v120 row_ror:4 row_mask:0xf bank_mask:0xf bound_ctrl:1
	v_add_f32_dpp v121, v121, v121 row_ror:4 row_mask:0xf bank_mask:0xf bound_ctrl:1
	s_nop 0
	v_add_f32_dpp v120, v120, v120 row_ror:8 row_mask:0xf bank_mask:0xf bound_ctrl:1
	v_pk_fma_f32 v[2:3], v[78:79], v[144:145], v[82:83] op_sel_hi:[1,0,1]
	v_pk_fma_f32 v[4:5], v[78:79], v[144:145], v[84:85] op_sel:[0,1,0] op_sel_hi:[1,1,1]
	v_pk_fma_f32 v[6:7], v[78:79], v[146:147], v[86:87] op_sel_hi:[1,0,1]
	v_pk_fma_f32 v[8:9], v[78:79], v[146:147], v[88:89] op_sel:[0,1,0] op_sel_hi:[1,1,1]
	v_add_f32_dpp v121, v121, v121 row_ror:8 row_mask:0xf bank_mask:0xf bound_ctrl:1
	global_store_dwordx2 v102, v[120:121], s[10:11]
	v_add_u32_e32 v102, s13, v102
	s_waitcnt lgkmcnt(5)
; #define LAS __attribute__((address_space(3)))
; __device__ __forceinline__ void phase_scan(CParams& P, LAS unsigned char* lds) {
;     ...
; #pragma unroll 2
;                 for (int j = 0; j < CH; j += 2) { const LAS float* sp = base + j * STEPF;
;                     SC_LOAD(B, sp + STEPF); SC_STEP(A);
;                     SC_LOAD(A, sp + 2 * STEPF);
;                     SC_STEP(B); }
	v_pk_mul_f32 v[78:79], v[2:3], v[10:11] op_sel_hi:[1,0]
	v_pk_mul_f32 v[96:97], v[2:3], v[148:149] op_sel_hi:[1,0]
	v_pk_fma_f32 v[78:79], v[4:5], v[10:11], v[78:79] op_sel:[0,1,0] op_sel_hi:[1,1,1]
	v_pk_fma_f32 v[96:97], v[4:5], v[148:149], v[96:97] op_sel:[0,1,0] op_sel_hi:[1,1,1]
	v_pk_fma_f32 v[78:79], v[6:7], v[12:13], v[78:79] op_sel_hi:[1,0,1]
	v_pk_fma_f32 v[96:97], v[6:7], v[150:151], v[96:97] op_sel_hi:[1,0,1]
	v_pk_fma_f32 v[78:79], v[8:9], v[12:13], v[78:79] op_sel:[0,1,0] op_sel_hi:[1,1,1]
	v_pk_mul_f32 v[82:83], v[70:71], v[18:19] op_sel_hi:[1,0]
	v_pk_fma_f32 v[96:97], v[8:9], v[150:151], v[96:97] op_sel:[0,1,0] op_sel_hi:[1,1,1]
	v_pk_mul_f32 v[84:85], v[70:71], v[18:19] op_sel:[0,1] op_sel_hi:[1,1]
	v_add_f32_dpp v78, v78, v78 quad_perm:[1,0,3,2] row_mask:0xf bank_mask:0xf bound_ctrl:1
	v_add_f32_dpp v79, v79, v79 quad_perm:[1,0,3,2] row_mask:0xf bank_mask:0xf bound_ctrl:1
	v_pk_mul_f32 v[86:87], v[70:71], v[20:21] op_sel_hi:[1,0]
	ds_read_b128 v[132:135], v100 offset:33280
	v_add_f32_dpp v78, v78, v78 quad_perm:[2,3,0,1] row_mask:0xf bank_mask:0xf bound_ctrl:1
	v_add_f32_dpp v79, v79, v79 quad_perm:[2,3,0,1] row_mask:0xf bank_mask:0xf bound_ctrl:1
	v_pk_mul_f32 v[88:89], v[70:71], v[20:21] op_sel:[0,1] op_sel_hi:[1,1]
	ds_read_b128 v[140:143], v100 offset:33792
	v_add_f32_dpp v78, v78, v78 row_half_mirror row_mask:0xf bank_mask:0xf bound_ctrl:1
	v_add_f32_dpp v79, v79, v79 row_half_mirror row_mask:0xf bank_mask:0xf bound_ctrl:1
	v_pk_fma_f32 v[82:83], v[2:3], v[14:15], v[82:83] op_sel_hi:[1,0,1]
	ds_read_b128 v[136:139], v100 offset:33536
	v_add_f32_dpp v78, v78, v78 row_mirror row_mask:0xf bank_mask:0xf bound_ctrl:1
	v_add_f32_dpp v79, v79, v79 row_mirror row_mask:0xf bank_mask:0xf bound_ctrl:1
	v_pk_fma_f32 v[84:85], v[4:5], v[14:15], v[84:85] op_sel:[0,1,0] op_sel_hi:[1,1,1]
	ds_read_b128 v[144:147], v100 offset:34048
	v_pk_fma_f32 v[86:87], v[6:7], v[16:17], v[86:87] op_sel_hi:[1,0,1]
	ds_read_b128 v[148:151], v100 offset:34304
	v_pk_fma_f32 v[88:89], v[8:9], v[16:17], v[88:89] op_sel:[0,1,0] op_sel_hi:[1,1,1]
	ds_read_b128 v[74:77], v101 offset:208
	v_cndmask_b32_e64 v104, v90, v92, s[50:51]
	v_cndmask_b32_e64 v106, v92, v90, s[50:51]
	v_cndmask_b32_e64 v108, v94, v96, s[50:51]
	v_pk_fma_f32 v[2:3], v[78:79], v[22:23], v[82:83] op_sel_hi:[1,0,1]
	v_pk_fma_f32 v[4:5], v[78:79], v[22:23], v[84:85] op_sel:[0,1,0] op_sel_hi:[1,1,1]
	v_pk_fma_f32 v[6:7], v[78:79], v[24:25], v[86:87] op_sel_hi:[1,0,1]
	v_pk_fma_f32 v[8:9], v[78:79], v[24:25], v[88:89] op_sel:[0,1,0] op_sel_hi:[1,1,1]
	v_cndmask_b32_e64 v110, v96, v94, s[50:51]
	v_cndmask_b32_e64 v105, v91, v93, s[50:51]
	v_cndmask_b32_e64 v107, v93, v91, s[50:51]
	s_waitcnt lgkmcnt(6)
	v_pk_mul_f32 v[78:79], v[2:3], v[30:31] op_sel_hi:[1,0]
	v_pk_mul_f32 v[90:91], v[2:3], v[26:27] op_sel_hi:[1,0]
	v_pk_fma_f32 v[78:79], v[4:5], v[30:31], v[78:79] op_sel:[0,1,0] op_sel_hi:[1,1,1]
	v_pk_fma_f32 v[90:91], v[4:5], v[26:27], v[90:91] op_sel:[0,1,0] op_sel_hi:[1,1,1]
	v_pk_fma_f32 v[78:79], v[6:7], v[32:33], v[78:79] op_sel_hi:[1,0,1]
	v_pk_fma_f32 v[90:91], v[6:7], v[28:29], v[90:91] op_sel_hi:[1,0,1]
	v_pk_fma_f32 v[78:79], v[8:9], v[32:33], v[78:79] op_sel:[0,1,0] op_sel_hi:[1,1,1]
	v_pk_mul_f32 v[82:83], v[72:73], v[38:39] op_sel_hi:[1,0]
	v_pk_fma_f32 v[90:91], v[8:9], v[28:29], v[90:91] op_sel:[0,1,0] op_sel_hi:[1,1,1]
	v_pk_mul_f32 v[84:85], v[72:73], v[38:39] op_sel:[0,1] op_sel_hi:[1,1]
	v_add_f32_dpp v78, v78, v78 quad_perm:[1,0,3,2] row_mask:0xf bank_mask:0xf bound_ctrl:1
	v_add_f32_dpp v79, v79, v79 quad_perm:[1,0,3,2] row_mask:0xf bank_mask:0xf bound_ctrl:1
	v_pk_mul_f32 v[86:87], v[72:73], v[40:41] op_sel_hi:[1,0]
	ds_read_b128 v[10:13], v100 offset:34560
	v_add_f32_dpp v78, v78, v78 quad_perm:[2,3,0,1] row_mask:0xf bank_mask:0xf bound_ctrl:1
	v_add_f32_dpp v79, v79, v79 quad_perm:[2,3,0,1] row_mask:0xf bank_mask:0xf bound_ctrl:1
	v_pk_mul_f32 v[88:89], v[72:73], v[40:41] op_sel:[0,1] op_sel_hi:[1,1]
	ds_read_b128 v[18:21], v100 offset:35072
	v_add_f32_dpp v78, v78, v78 row_half_mirror row_mask:0xf bank_mask:0xf bound_ctrl:1
	v_add_f32_dpp v79, v79, v79 row_half_mirror row_mask:0xf bank_mask:0xf bound_ctrl:1
	v_pk_fma_f32 v[82:83], v[2:3], v[34:35], v[82:83] op_sel_hi:[1,0,1]
	ds_read_b128 v[14:17], v100 offset:34816
	v_add_f32_dpp v78, v78, v78 row_mirror row_mask:0xf bank_mask:0xf bound_ctrl:1
	v_add_f32_dpp v79, v79, v79 row_mirror row_mask:0xf bank_mask:0xf bound_ctrl:1
	v_pk_fma_f32 v[84:85], v[4:5], v[34:35], v[84:85] op_sel:[0,1,0] op_sel_hi:[1,1,1]
	ds_read_b128 v[22:25], v100 offset:35328
	v_pk_fma_f32 v[86:87], v[6:7], v[36:37], v[86:87] op_sel_hi:[1,0,1]
	ds_read_b128 v[26:29], v100 offset:35584
	v_pk_fma_f32 v[88:89], v[8:9], v[36:37], v[88:89] op_sel:[0,1,0] op_sel_hi:[1,1,1]
	v_cndmask_b32_e64 v109, v95, v97, s[50:51]
	v_cndmask_b32_e64 v111, v97, v95, s[50:51]
	v_add_f32_dpp v112, v106, v104 quad_perm:[1,0,3,2] row_mask:0xf bank_mask:0xf bound_ctrl:1
	v_pk_fma_f32 v[2:3], v[78:79], v[42:43], v[82:83] op_sel_hi:[1,0,1]
	v_pk_fma_f32 v[4:5], v[78:79], v[42:43], v[84:85] op_sel:[0,1,0] op_sel_hi:[1,1,1]
	v_pk_fma_f32 v[6:7], v[78:79], v[44:45], v[86:87] op_sel_hi:[1,0,1]
	v_pk_fma_f32 v[8:9], v[78:79], v[44:45], v[88:89] op_sel:[0,1,0] op_sel_hi:[1,1,1]
	v_add_f32_dpp v114, v110, v108 quad_perm:[1,0,3,2] row_mask:0xf bank_mask:0xf bound_ctrl:1
	v_add_f32_dpp v113, v107, v105 quad_perm:[1,0,3,2] row_mask:0xf bank_mask:0xf bound_ctrl:1
	v_add_f32_dpp v115, v111, v109 quad_perm:[1,0,3,2] row_mask:0xf bank_mask:0xf bound_ctrl:1
	s_waitcnt lgkmcnt(5)
; #define LAS __attribute__((address_space(3)))
; __device__ __forceinline__ void phase_scan(CParams& P, LAS unsigned char* lds) {
;     ...
; #pragma unroll 2
;                 for (int j = 0; j < CH; j += 2) { const LAS float* sp = base + j * STEPF;
;                     SC_LOAD(B, sp + STEPF); SC_STEP(A);
;                     SC_LOAD(A, sp + 2 * STEPF);
;                     SC_STEP(B); }
	v_pk_mul_f32 v[78:79], v[2:3], v[132:133] op_sel_hi:[1,0]
	v_pk_mul_f32 v[92:93], v[2:3], v[46:47] op_sel_hi:[1,0]
	v_pk_fma_f32 v[78:79], v[4:5], v[132:133], v[78:79] op_sel:[0,1,0] op_sel_hi:[1,1,1]
	v_pk_fma_f32 v[92:93], v[4:5], v[46:47], v[92:93] op_sel:[0,1,0] op_sel_hi:[1,1,1]
	v_pk_fma_f32 v[78:79], v[6:7], v[134:135], v[78:79] op_sel_hi:[1,0,1]
	v_pk_fma_f32 v[92:93], v[6:7], v[48:49], v[92:93] op_sel_hi:[1,0,1]
	v_pk_fma_f32 v[78:79], v[8:9], v[134:135], v[78:79] op_sel:[0,1,0] op_sel_hi:[1,1,1]
	v_pk_mul_f32 v[82:83], v[74:75], v[140:141] op_sel_hi:[1,0]
	v_pk_fma_f32 v[92:93], v[8:9], v[48:49], v[92:93] op_sel:[0,1,0] op_sel_hi:[1,1,1]
	v_pk_mul_f32 v[84:85], v[74:75], v[140:141] op_sel:[0,1] op_sel_hi:[1,1]
	v_add_f32_dpp v78, v78, v78 quad_perm:[1,0,3,2] row_mask:0xf bank_mask:0xf bound_ctrl:1
	v_add_f32_dpp v79, v79, v79 quad_perm:[1,0,3,2] row_mask:0xf bank_mask:0xf bound_ctrl:1
	v_pk_mul_f32 v[86:87], v[74:75], v[142:143] op_sel_hi:[1,0]
	ds_read_b128 v[30:33], v100 offset:35840
	v_add_f32_dpp v78, v78, v78 quad_perm:[2,3,0,1] row_mask:0xf bank_mask:0xf bound_ctrl:1
	v_add_f32_dpp v79, v79, v79 quad_perm:[2,3,0,1] row_mask:0xf bank_mask:0xf bound_ctrl:1
	v_pk_mul_f32 v[88:89], v[74:75], v[142:143] op_sel:[0,1] op_sel_hi:[1,1]
	ds_read_b128 v[38:41], v100 offset:36352
	v_add_f32_dpp v78, v78, v78 row_half_mirror row_mask:0xf bank_mask:0xf bound_ctrl:1
	v_add_f32_dpp v79, v79, v79 row_half_mirror row_mask:0xf bank_mask:0xf bound_ctrl:1
	v_pk_fma_f32 v[82:83], v[2:3], v[136:137], v[82:83] op_sel_hi:[1,0,1]
	ds_read_b128 v[34:37], v100 offset:36096
	v_add_f32_dpp v78, v78, v78 row_mirror row_mask:0xf bank_mask:0xf bound_ctrl:1
	v_add_f32_dpp v79, v79, v79 row_mirror row_mask:0xf bank_mask:0xf bound_ctrl:1
	v_pk_fma_f32 v[84:85], v[4:5], v[136:137], v[84:85] op_sel:[0,1,0] op_sel_hi:[1,1,1]
	ds_read_b128 v[42:45], v100 offset:36608
	v_pk_fma_f32 v[86:87], v[6:7], v[138:139], v[86:87] op_sel_hi:[1,0,1]
	ds_read_b128 v[46:49], v100 offset:36864
	v_pk_fma_f32 v[88:89], v[8:9], v[138:139], v[88:89] op_sel:[0,1,0] op_sel_hi:[1,1,1]
	ds_read_b128 v[70:73], v101 offset:224
	v_cndmask_b32_e64 v116, v112, v114, s[52:53]
	v_cndmask_b32_e64 v118, v114, v112, s[52:53]
	v_cndmask_b32_e64 v117, v113, v115, s[52:53]
	v_pk_fma_f32 v[2:3], v[78:79], v[144:145], v[82:83] op_sel_hi:[1,0,1]
	v_pk_fma_f32 v[4:5], v[78:79], v[144:145], v[84:85] op_sel:[0,1,0] op_sel_hi:[1,1,1]
	v_pk_fma_f32 v[6:7], v[78:79], v[146:147], v[86:87] op_sel_hi:[1,0,1]
	v_pk_fma_f32 v[8:9], v[78:79], v[146:147], v[88:89] op_sel:[0,1,0] op_sel_hi:[1,1,1]
	v_cndmask_b32_e64 v119, v115, v113, s[52:53]
	v_add_f32_dpp v120, v118, v116 quad_perm:[2,3,0,1] row_mask:0xf bank_mask:0xf bound_ctrl:1
	s_nop 0
	v_add_f32_dpp v121, v119, v117 quad_perm:[2,3,0,1] row_mask:0xf bank_mask:0xf bound_ctrl:1
	s_waitcnt lgkmcnt(6)
	v_pk_mul_f32 v[78:79], v[2:3], v[10:11] op_sel_hi:[1,0]
	v_pk_mul_f32 v[94:95], v[2:3], v[148:149] op_sel_hi:[1,0]
	v_pk_fma_f32 v[78:79], v[4:5], v[10:11], v[78:79] op_sel:[0,1,0] op_sel_hi:[1,1,1]
	v_pk_fma_f32 v[94:95], v[4:5], v[148:149], v[94:95] op_sel:[0,1,0] op_sel_hi:[1,1,1]
	v_pk_fma_f32 v[78:79], v[6:7], v[12:13], v[78:79] op_sel_hi:[1,0,1]
	v_pk_fma_f32 v[94:95], v[6:7], v[150:151], v[94:95] op_sel_hi:[1,0,1]
	v_pk_fma_f32 v[78:79], v[8:9], v[12:13], v[78:79] op_sel:[0,1,0] op_sel_hi:[1,1,1]
	v_pk_mul_f32 v[82:83], v[76:77], v[18:19] op_sel_hi:[1,0]
	v_pk_fma_f32 v[94:95], v[8:9], v[150:151], v[94:95] op_sel:[0,1,0] op_sel_hi:[1,1,1]
	v_pk_mul_f32 v[84:85], v[76:77], v[18:19] op_sel:[0,1] op_sel_hi:[1,1]
	v_add_f32_dpp v78, v78, v78 quad_perm:[1,0,3,2] row_mask:0xf bank_mask:0xf bound_ctrl:1
	v_add_f32_dpp v79, v79, v79 quad_perm:[1,0,3,2] row_mask:0xf bank_mask:0xf bound_ctrl:1
	v_pk_mul_f32 v[86:87], v[76:77], v[20:21] op_sel_hi:[1,0]
	ds_read_b128 v[132:135], v100 offset:37120
	v_add_f32_dpp v78, v78, v78 quad_perm:[2,3,0,1] row_mask:0xf bank_mask:0xf bound_ctrl:1
	v_add_f32_dpp v79, v79, v79 quad_perm:[2,3,0,1] row_mask:0xf bank_mask:0xf bound_ctrl:1
	v_pk_mul_f32 v[88:89], v[76:77], v[20:21] op_sel:[0,1] op_sel_hi:[1,1]
	ds_read_b128 v[140:143], v100 offset:37632
	v_add_f32_dpp v78, v78, v78 row_half_mirror row_mask:0xf bank_mask:0xf bound_ctrl:1
	v_add_f32_dpp v79, v79, v79 row_half_mirror row_mask:0xf bank_mask:0xf bound_ctrl:1
	v_pk_fma_f32 v[82:83], v[2:3], v[14:15], v[82:83] op_sel_hi:[1,0,1]
	ds_read_b128 v[136:139], v100 offset:37376
	v_add_f32_dpp v78, v78, v78 row_mirror row_mask:0xf bank_mask:0xf bound_ctrl:1
	v_add_f32_dpp v79, v79, v79 row_mirror row_mask:0xf bank_mask:0xf bound_ctrl:1
	v_pk_fma_f32 v[84:85], v[4:5], v[14:15], v[84:85] op_sel:[0,1,0] op_sel_hi:[1,1,1]
	ds_read_b128 v[144:147], v100 offset:37888
	v_pk_fma_f32 v[86:87], v[6:7], v[16:17], v[86:87] op_sel_hi:[1,0,1]
	ds_read_b128 v[148:151], v100 offset:38144
	v_pk_fma_f32 v[88:89], v[8:9], v[16:17], v[88:89] op_sel:[0,1,0] op_sel_hi:[1,1,1]
	v_add_f32_dpp v120, v120, v120 row_ror:4 row_mask:0xf bank_mask:0xf bound_ctrl:1
	v_add_f32_dpp v121, v121, v121 row_ror:4 row_mask:0xf bank_mask:0xf bound_ctrl:1
	s_nop 0
	v_add_f32_dpp v120, v120, v120 row_ror:8 row_mask:0xf bank_mask:0xf bound_ctrl:1
	v_pk_fma_f32 v[2:3], v[78:79], v[22:23], v[82:83] op_sel_hi:[1,0,1]
	v_pk_fma_f32 v[4:5], v[78:79], v[22:23], v[84:85] op_sel:[0,1,0] op_sel_hi:[1,1,1]
	v_pk_fma_f32 v[6:7], v[78:79], v[24:25], v[86:87] op_sel_hi:[1,0,1]
	v_pk_fma_f32 v[8:9], v[78:79], v[24:25], v[88:89] op_sel:[0,1,0] op_sel_hi:[1,1,1]
	v_add_f32_dpp v121, v121, v121 row_ror:8 row_mask:0xf bank_mask:0xf bound_ctrl:1
	global_store_dwordx2 v102, v[120:121], s[10:11]
	v_add_u32_e32 v102, s13, v102
	s_waitcnt lgkmcnt(5)
; #define LAS __attribute__((address_space(3)))
; __device__ __forceinline__ void phase_scan(CParams& P, LAS unsigned char* lds) {
;     ...
; #pragma unroll 2
;                 for (int j = 0; j < CH; j += 2) { const LAS float* sp = base + j * STEPF;
;                     SC_LOAD(B, sp + STEPF); SC_STEP(A);
;                     SC_LOAD(A, sp + 2 * STEPF);
;                     SC_STEP(B); }
	v_pk_mul_f32 v[78:79], v[2:3], v[30:31] op_sel_hi:[1,0]
	v_pk_mul_f32 v[96:97], v[2:3], v[26:27] op_sel_hi:[1,0]
	v_pk_fma_f32 v[78:79], v[4:5], v[30:31], v[78:79] op_sel:[0,1,0] op_sel_hi:[1,1,1]
	v_pk_fma_f32 v[96:97], v[4:5], v[26:27], v[96:97] op_sel:[0,1,0] op_sel_hi:[1,1,1]
	v_pk_fma_f32 v[78:79], v[6:7], v[32:33], v[78:79] op_sel_hi:[1,0,1]
	v_pk_fma_f32 v[96:97], v[6:7], v[28:29], v[96:97] op_sel_hi:[1,0,1]
	v_pk_fma_f32 v[78:79], v[8:9], v[32:33], v[78:79] op_sel:[0,1,0] op_sel_hi:[1,1,1]
	v_pk_mul_f32 v[82:83], v[70:71], v[38:39] op_sel_hi:[1,0]
	v_pk_fma_f32 v[96:97], v[8:9], v[28:29], v[96:97] op_sel:[0,1,0] op_sel_hi:[1,1,1]
	v_pk_mul_f32 v[84:85], v[70:71], v[38:39] op_sel:[0,1] op_sel_hi:[1,1]
	v_add_f32_dpp v78, v78, v78 quad_perm:[1,0,3,2] row_mask:0xf bank_mask:0xf bound_ctrl:1
	v_add_f32_dpp v79, v79, v79 quad_perm:[1,0,3,2] row_mask:0xf bank_mask:0xf bound_ctrl:1
	v_pk_mul_f32 v[86:87], v[70:71], v[40:41] op_sel_hi:[1,0]
	ds_read_b128 v[10:13], v100 offset:38400
	v_add_f32_dpp v78, v78, v78 quad_perm:[2,3,0,1] row_mask:0xf bank_mask:0xf bound_ctrl:1
	v_add_f32_dpp v79, v79, v79 quad_perm:[2,3,0,1] row_mask:0xf bank_mask:0xf bound_ctrl:1
	v_pk_mul_f32 v[88:89], v[70:71], v[40:41] op_sel:[0,1] op_sel_hi:[1,1]
	ds_read_b128 v[18:21], v100 offset:38912
	v_add_f32_dpp v78, v78, v78 row_half_mirror row_mask:0xf bank_mask:0xf bound_ctrl:1
	v_add_f32_dpp v79, v79, v79 row_half_mirror row_mask:0xf bank_mask:0xf bound_ctrl:1
	v_pk_fma_f32 v[82:83], v[2:3], v[34:35], v[82:83] op_sel_hi:[1,0,1]
	ds_read_b128 v[14:17], v100 offset:38656
	v_add_f32_dpp v78, v78, v78 row_mirror row_mask:0xf bank_mask:0xf bound_ctrl:1
	v_add_f32_dpp v79, v79, v79 row_mirror row_mask:0xf bank_mask:0xf bound_ctrl:1
	v_pk_fma_f32 v[84:85], v[4:5], v[34:35], v[84:85] op_sel:[0,1,0] op_sel_hi:[1,1,1]
	ds_read_b128 v[22:25], v100 offset:39168
	v_pk_fma_f32 v[86:87], v[6:7], v[36:37], v[86:87] op_sel_hi:[1,0,1]
	ds_read_b128 v[26:29], v100 offset:39424
	v_pk_fma_f32 v[88:89], v[8:9], v[36:37], v[88:89] op_sel:[0,1,0] op_sel_hi:[1,1,1]
	ds_read_b128 v[74:77], v101 offset:240
	v_cndmask_b32_e64 v104, v90, v92, s[50:51]
	v_cndmask_b32_e64 v106, v92, v90, s[50:51]
	v_cndmask_b32_e64 v108, v94, v96, s[50:51]
	v_pk_fma_f32 v[2:3], v[78:79], v[42:43], v[82:83] op_sel_hi:[1,0,1]
	v_pk_fma_f32 v[4:5], v[78:79], v[42:43], v[84:85] op_sel:[0,1,0] op_sel_hi:[1,1,1]
	v_pk_fma_f32 v[6:7], v[78:79], v[44:45], v[86:87] op_sel_hi:[1,0,1]
	v_pk_fma_f32 v[8:9], v[78:79], v[44:45], v[88:89] op_sel:[0,1,0] op_sel_hi:[1,1,1]
	v_cndmask_b32_e64 v110, v96, v94, s[50:51]
	v_cndmask_b32_e64 v105, v91, v93, s[50:51]
	v_cndmask_b32_e64 v107, v93, v91, s[50:51]
	s_waitcnt lgkmcnt(6)
	v_pk_mul_f32 v[78:79], v[2:3], v[132:133] op_sel_hi:[1,0]
	v_pk_mul_f32 v[90:91], v[2:3], v[46:47] op_sel_hi:[1,0]
	v_pk_fma_f32 v[78:79], v[4:5], v[132:133], v[78:79] op_sel:[0,1,0] op_sel_hi:[1,1,1]
	v_pk_fma_f32 v[90:91], v[4:5], v[46:47], v[90:91] op_sel:[0,1,0] op_sel_hi:[1,1,1]
	v_pk_fma_f32 v[78:79], v[6:7], v[134:135], v[78:79] op_sel_hi:[1,0,1]
	v_pk_fma_f32 v[90:91], v[6:7], v[48:49], v[90:91] op_sel_hi:[1,0,1]
	v_pk_fma_f32 v[78:79], v[8:9], v[134:135], v[78:79] op_sel:[0,1,0] op_sel_hi:[1,1,1]
	v_pk_mul_f32 v[82:83], v[72:73], v[140:141] op_sel_hi:[1,0]
	v_pk_fma_f32 v[90:91], v[8:9], v[48:49], v[90:91] op_sel:[0,1,0] op_sel_hi:[1,1,1]
	v_pk_mul_f32 v[84:85], v[72:73], v[140:141] op_sel:[0,1] op_sel_hi:[1,1]
	v_add_f32_dpp v78, v78, v78 quad_perm:[1,0,3,2] row_mask:0xf bank_mask:0xf bound_ctrl:1
	v_add_f32_dpp v79, v79, v79 quad_perm:[1,0,3,2] row_mask:0xf bank_mask:0xf bound_ctrl:1
	v_pk_mul_f32 v[86:87], v[72:73], v[142:143] op_sel_hi:[1,0]
	ds_read_b128 v[30:33], v100 offset:39680
	v_add_f32_dpp v78, v78, v78 quad_perm:[2,3,0,1] row_mask:0xf bank_mask:0xf bound_ctrl:1
	v_add_f32_dpp v79, v79, v79 quad_perm:[2,3,0,1] row_mask:0xf bank_mask:0xf bound_ctrl:1
	v_pk_mul_f32 v[88:89], v[72:73], v[142:143] op_sel:[0,1] op_sel_hi:[1,1]
	ds_read_b128 v[38:41], v100 offset:40192
	v_add_f32_dpp v78, v78, v78 row_half_mirror row_mask:0xf bank_mask:0xf bound_ctrl:1
	v_add_f32_dpp v79, v79, v79 row_half_mirror row_mask:0xf bank_mask:0xf bound_ctrl:1
	v_pk_fma_f32 v[82:83], v[2:3], v[136:137], v[82:83] op_sel_hi:[1,0,1]
	ds_read_b128 v[34:37], v100 offset:39936
	v_add_f32_dpp v78, v78, v78 row_mirror row_mask:0xf bank_mask:0xf bound_ctrl:1
	v_add_f32_dpp v79, v79, v79 row_mirror row_mask:0xf bank_mask:0xf bound_ctrl:1
	v_pk_fma_f32 v[84:85], v[4:5], v[136:137], v[84:85] op_sel:[0,1,0] op_sel_hi:[1,1,1]
	ds_read_b128 v[42:45], v100 offset:40448
	v_pk_fma_f32 v[86:87], v[6:7], v[138:139], v[86:87] op_sel_hi:[1,0,1]
	ds_read_b128 v[46:49], v100 offset:40704
	v_pk_fma_f32 v[88:89], v[8:9], v[138:139], v[88:89] op_sel:[0,1,0] op_sel_hi:[1,1,1]
	v_cndmask_b32_e64 v109, v95, v97, s[50:51]
	v_cndmask_b32_e64 v111, v97, v95, s[50:51]
	v_add_f32_dpp v112, v106, v104 quad_perm:[1,0,3,2] row_mask:0xf bank_mask:0xf bound_ctrl:1
	v_pk_fma_f32 v[2:3], v[78:79], v[144:145], v[82:83] op_sel_hi:[1,0,1]
	v_pk_fma_f32 v[4:5], v[78:79], v[144:145], v[84:85] op_sel:[0,1,0] op_sel_hi:[1,1,1]
	v_pk_fma_f32 v[6:7], v[78:79], v[146:147], v[86:87] op_sel_hi:[1,0,1]
	v_pk_fma_f32 v[8:9], v[78:79], v[146:147], v[88:89] op_sel:[0,1,0] op_sel_hi:[1,1,1]
	v_add_f32_dpp v114, v110, v108 quad_perm:[1,0,3,2] row_mask:0xf bank_mask:0xf bound_ctrl:1
	v_add_f32_dpp v113, v107, v105 quad_perm:[1,0,3,2] row_mask:0xf bank_mask:0xf bound_ctrl:1
	v_add_f32_dpp v115, v111, v109 quad_perm:[1,0,3,2] row_mask:0xf bank_mask:0xf bound_ctrl:1
	s_waitcnt lgkmcnt(5)
; #define LAS __attribute__((address_space(3)))
; __device__ __forceinline__ void phase_scan(CParams& P, LAS unsigned char* lds) {
;     ...
;             for (int c = 0; c < NCH; ++c) {
;                 __syncthreads();
;                 const LAS float* base = lf + (c & 1) * BUFF + 8 * oct;
;                 SC_LOAD(A, base);
; #pragma unroll 2
;                 for (int j = 0; j < CH; j += 2) { const LAS float* sp = base + j * STEPF;
;                     SC_LOAD(B, sp + STEPF); SC_STEP(A);
;                     SC_LOAD(A, sp + 2 * STEPF);
;                     SC_STEP(B); }
;             }
	v_pk_mul_f32 v[78:79], v[2:3], v[10:11] op_sel_hi:[1,0]
	v_pk_mul_f32 v[92:93], v[2:3], v[148:149] op_sel_hi:[1,0]
	v_pk_fma_f32 v[78:79], v[4:5], v[10:11], v[78:79] op_sel:[0,1,0] op_sel_hi:[1,1,1]
	v_pk_fma_f32 v[92:93], v[4:5], v[148:149], v[92:93] op_sel:[0,1,0] op_sel_hi:[1,1,1]
	v_pk_fma_f32 v[78:79], v[6:7], v[12:13], v[78:79] op_sel_hi:[1,0,1]
	v_pk_fma_f32 v[92:93], v[6:7], v[150:151], v[92:93] op_sel_hi:[1,0,1]
	v_pk_fma_f32 v[78:79], v[8:9], v[12:13], v[78:79] op_sel:[0,1,0] op_sel_hi:[1,1,1]
	v_pk_mul_f32 v[82:83], v[74:75], v[18:19] op_sel_hi:[1,0]
	v_pk_fma_f32 v[92:93], v[8:9], v[150:151], v[92:93] op_sel:[0,1,0] op_sel_hi:[1,1,1]
	v_pk_mul_f32 v[84:85], v[74:75], v[18:19] op_sel:[0,1] op_sel_hi:[1,1]
	v_add_f32_dpp v78, v78, v78 quad_perm:[1,0,3,2] row_mask:0xf bank_mask:0xf bound_ctrl:1
	v_add_f32_dpp v79, v79, v79 quad_perm:[1,0,3,2] row_mask:0xf bank_mask:0xf bound_ctrl:1
	v_pk_mul_f32 v[86:87], v[74:75], v[20:21] op_sel_hi:[1,0]
	v_add_f32_dpp v78, v78, v78 quad_perm:[2,3,0,1] row_mask:0xf bank_mask:0xf bound_ctrl:1
	v_add_f32_dpp v79, v79, v79 quad_perm:[2,3,0,1] row_mask:0xf bank_mask:0xf bound_ctrl:1
	v_pk_mul_f32 v[88:89], v[74:75], v[20:21] op_sel:[0,1] op_sel_hi:[1,1]
	v_add_f32_dpp v78, v78, v78 row_half_mirror row_mask:0xf bank_mask:0xf bound_ctrl:1
	v_add_f32_dpp v79, v79, v79 row_half_mirror row_mask:0xf bank_mask:0xf bound_ctrl:1
	v_pk_fma_f32 v[82:83], v[2:3], v[14:15], v[82:83] op_sel_hi:[1,0,1]
	v_add_f32_dpp v78, v78, v78 row_mirror row_mask:0xf bank_mask:0xf bound_ctrl:1
	v_add_f32_dpp v79, v79, v79 row_mirror row_mask:0xf bank_mask:0xf bound_ctrl:1
	v_pk_fma_f32 v[84:85], v[4:5], v[14:15], v[84:85] op_sel:[0,1,0] op_sel_hi:[1,1,1]
	v_pk_fma_f32 v[86:87], v[6:7], v[16:17], v[86:87] op_sel_hi:[1,0,1]
	v_pk_fma_f32 v[88:89], v[8:9], v[16:17], v[88:89] op_sel:[0,1,0] op_sel_hi:[1,1,1]
	v_cndmask_b32_e64 v116, v112, v114, s[52:53]
	v_cndmask_b32_e64 v118, v114, v112, s[52:53]
	v_cndmask_b32_e64 v117, v113, v115, s[52:53]
	v_pk_fma_f32 v[2:3], v[78:79], v[22:23], v[82:83] op_sel_hi:[1,0,1]
	v_pk_fma_f32 v[4:5], v[78:79], v[22:23], v[84:85] op_sel:[0,1,0] op_sel_hi:[1,1,1]
	v_pk_fma_f32 v[6:7], v[78:79], v[24:25], v[86:87] op_sel_hi:[1,0,1]
	v_pk_fma_f32 v[8:9], v[78:79], v[24:25], v[88:89] op_sel:[0,1,0] op_sel_hi:[1,1,1]
	v_cndmask_b32_e64 v119, v115, v113, s[52:53]
	v_add_f32_dpp v120, v118, v116 quad_perm:[2,3,0,1] row_mask:0xf bank_mask:0xf bound_ctrl:1
	s_nop 0
	v_add_f32_dpp v121, v119, v117 quad_perm:[2,3,0,1] row_mask:0xf bank_mask:0xf bound_ctrl:1
	s_waitcnt lgkmcnt(0)
	v_pk_mul_f32 v[78:79], v[2:3], v[30:31] op_sel_hi:[1,0]
	v_pk_mul_f32 v[94:95], v[2:3], v[26:27] op_sel_hi:[1,0]
	v_pk_fma_f32 v[78:79], v[4:5], v[30:31], v[78:79] op_sel:[0,1,0] op_sel_hi:[1,1,1]
	v_pk_fma_f32 v[94:95], v[4:5], v[26:27], v[94:95] op_sel:[0,1,0] op_sel_hi:[1,1,1]
	v_pk_fma_f32 v[78:79], v[6:7], v[32:33], v[78:79] op_sel_hi:[1,0,1]
	v_pk_fma_f32 v[94:95], v[6:7], v[28:29], v[94:95] op_sel_hi:[1,0,1]
	v_pk_fma_f32 v[78:79], v[8:9], v[32:33], v[78:79] op_sel:[0,1,0] op_sel_hi:[1,1,1]
	v_pk_mul_f32 v[82:83], v[76:77], v[38:39] op_sel_hi:[1,0]
	v_pk_fma_f32 v[94:95], v[8:9], v[28:29], v[94:95] op_sel:[0,1,0] op_sel_hi:[1,1,1]
	v_pk_mul_f32 v[84:85], v[76:77], v[38:39] op_sel:[0,1] op_sel_hi:[1,1]
	v_add_f32_dpp v78, v78, v78 quad_perm:[1,0,3,2] row_mask:0xf bank_mask:0xf bound_ctrl:1
	v_add_f32_dpp v79, v79, v79 quad_perm:[1,0,3,2] row_mask:0xf bank_mask:0xf bound_ctrl:1
	v_pk_mul_f32 v[86:87], v[76:77], v[40:41] op_sel_hi:[1,0]
	v_add_f32_dpp v78, v78, v78 quad_perm:[2,3,0,1] row_mask:0xf bank_mask:0xf bound_ctrl:1
	v_add_f32_dpp v79, v79, v79 quad_perm:[2,3,0,1] row_mask:0xf bank_mask:0xf bound_ctrl:1
	v_pk_mul_f32 v[88:89], v[76:77], v[40:41] op_sel:[0,1] op_sel_hi:[1,1]
	v_add_f32_dpp v78, v78, v78 row_half_mirror row_mask:0xf bank_mask:0xf bound_ctrl:1
	v_add_f32_dpp v79, v79, v79 row_half_mirror row_mask:0xf bank_mask:0xf bound_ctrl:1
	v_pk_fma_f32 v[82:83], v[2:3], v[34:35], v[82:83] op_sel_hi:[1,0,1]
	v_add_f32_dpp v78, v78, v78 row_mirror row_mask:0xf bank_mask:0xf bound_ctrl:1
	v_add_f32_dpp v79, v79, v79 row_mirror row_mask:0xf bank_mask:0xf bound_ctrl:1
	v_pk_fma_f32 v[84:85], v[4:5], v[34:35], v[84:85] op_sel:[0,1,0] op_sel_hi:[1,1,1]
	v_pk_fma_f32 v[86:87], v[6:7], v[36:37], v[86:87] op_sel_hi:[1,0,1]
	v_pk_fma_f32 v[88:89], v[8:9], v[36:37], v[88:89] op_sel:[0,1,0] op_sel_hi:[1,1,1]
	v_add_f32_dpp v120, v120, v120 row_ror:4 row_mask:0xf bank_mask:0xf bound_ctrl:1
	v_add_f32_dpp v121, v121, v121 row_ror:4 row_mask:0xf bank_mask:0xf bound_ctrl:1
	s_nop 0
	v_add_f32_dpp v120, v120, v120 row_ror:8 row_mask:0xf bank_mask:0xf bound_ctrl:1
	v_pk_fma_f32 v[2:3], v[78:79], v[42:43], v[82:83] op_sel_hi:[1,0,1]
	v_pk_fma_f32 v[4:5], v[78:79], v[42:43], v[84:85] op_sel:[0,1,0] op_sel_hi:[1,1,1]
	v_pk_fma_f32 v[6:7], v[78:79], v[44:45], v[86:87] op_sel_hi:[1,0,1]
	v_pk_fma_f32 v[8:9], v[78:79], v[44:45], v[88:89] op_sel:[0,1,0] op_sel_hi:[1,1,1]
	v_add_f32_dpp v121, v121, v121 row_ror:8 row_mask:0xf bank_mask:0xf bound_ctrl:1
	global_store_dwordx2 v102, v[120:121], s[10:11]
	v_add_u32_e32 v102, s13, v102
	v_pk_mul_f32 v[96:97], v[2:3], v[46:47] op_sel_hi:[1,0]
	v_pk_fma_f32 v[96:97], v[4:5], v[46:47], v[96:97] op_sel:[0,1,0] op_sel_hi:[1,1,1]
	v_pk_fma_f32 v[96:97], v[6:7], v[48:49], v[96:97] op_sel_hi:[1,0,1]
	v_pk_fma_f32 v[96:97], v[8:9], v[48:49], v[96:97] op_sel:[0,1,0] op_sel_hi:[1,1,1]
	v_cndmask_b32_e64 v104, v90, v92, s[50:51]
	v_cndmask_b32_e64 v106, v92, v90, s[50:51]
	v_cndmask_b32_e64 v108, v94, v96, s[50:51]
	v_cndmask_b32_e64 v110, v96, v94, s[50:51]
	v_cndmask_b32_e64 v105, v91, v93, s[50:51]
	v_cndmask_b32_e64 v107, v93, v91, s[50:51]
	v_cndmask_b32_e64 v109, v95, v97, s[50:51]
	v_cndmask_b32_e64 v111, v97, v95, s[50:51]
	v_add_f32_dpp v112, v106, v104 quad_perm:[1,0,3,2] row_mask:0xf bank_mask:0xf bound_ctrl:1
	v_add_f32_dpp v114, v110, v108 quad_perm:[1,0,3,2] row_mask:0xf bank_mask:0xf bound_ctrl:1
	v_add_f32_dpp v113, v107, v105 quad_perm:[1,0,3,2] row_mask:0xf bank_mask:0xf bound_ctrl:1
	v_add_f32_dpp v115, v111, v109 quad_perm:[1,0,3,2] row_mask:0xf bank_mask:0xf bound_ctrl:1
	v_cndmask_b32_e64 v116, v112, v114, s[52:53]
	v_cndmask_b32_e64 v118, v114, v112, s[52:53]
	v_cndmask_b32_e64 v117, v113, v115, s[52:53]
	v_cndmask_b32_e64 v119, v115, v113, s[52:53]
	v_add_f32_dpp v120, v118, v116 quad_perm:[2,3,0,1] row_mask:0xf bank_mask:0xf bound_ctrl:1
	s_nop 0
	v_add_f32_dpp v121, v119, v117 quad_perm:[2,3,0,1] row_mask:0xf bank_mask:0xf bound_ctrl:1
	v_add_f32_dpp v120, v120, v120 row_ror:4 row_mask:0xf bank_mask:0xf bound_ctrl:1
	s_nop 0
	v_add_f32_dpp v121, v121, v121 row_ror:4 row_mask:0xf bank_mask:0xf bound_ctrl:1
	v_add_f32_dpp v120, v120, v120 row_ror:8 row_mask:0xf bank_mask:0xf bound_ctrl:1
	s_nop 0
	v_add_f32_dpp v121, v121, v121 row_ror:8 row_mask:0xf bank_mask:0xf bound_ctrl:1
	global_store_dwordx2 v102, v[120:121], s[10:11]
	v_add_u32_e32 v102, s13, v102
	s_xor_b32 s14, s14, 0xc000
	s_add_i32 s12, s12, 1
	s_cmp_lt_u32 s12, 0x80
	s_cbranch_scc1 .Lr3_chunk
; __device__ __forceinline__ void phase_scan(CParams& P, LAS unsigned char* lds) {
;     ...
;             __builtin_amdgcn_s_setprio(0);
;             __syncthreads();
;         }
;     }
;     __syncthreads();
	s_branch .LBB0_626

; __device__ __forceinline__ int tid_() { int t = threadIdx.x; asm volatile("" : "+v"(t)); return t; }
; __device__ __forceinline__ int bid_() { int b = blockIdx.x; asm volatile("" : "+s"(b)); return b; }
; __device__ __forceinline__ int nblk_() { int g = gridDim.x; asm volatile("" : "+s"(g)); return g; }
; __device__ __forceinline__ void phase_attn(CParams& P, LAS unsigned char* lds) {
;     const int tid = tid_(), lane = tid & 63, wid = tid >> 6, ql = lane & 31, hi = lane >> 5;
;     const bf16_t* Q = (const bf16_t*)(P.ws + WS_Q); const bf16_t* KF = (const bf16_t*)(P.ws + WS_KF); const bf16_t* VT = (const bf16_t*)(P.ws + WS_VT); bf16_t* O = (bf16_t*)(P.ws + WS_OATT);
;     const int G = nblk_(), bx = bid_(); const int vcu = (G % 8 == 0) ? (bx % 8) * (G / 8) + bx / 8 : bx;
;     ...
;     for (int u = vcu; u < GSEQ * 8 * 16; u += G) {
;         const int sh = u >> 4, qb = u & 15, s = sh >> 3, h = sh & 7; const size_t tok0 = (size_t)s * SEQ;
.LBB0_606:
	s_and_b64 vcc, exec, s[4:5]
	s_cbranch_vccz .LBB0_627
	s_lshr_b32 s4, s2, 3
	s_cmp_ge_u32 s4, 16
	s_cbranch_scc1 .Lr3_scan
	s_waitcnt vmcnt(0)
	v_mov_b32_e32 v0, v222
	s_load_dword s10, s[80:81], 0x0
	s_waitcnt lgkmcnt(0)
	s_movk_i32 s10, 0x80
	s_and_b32 s4, s10, 7
	s_mov_b32 s11, s2
	s_cmp_lg_u32 s4, 0
	s_cbranch_scc1 .LBB0_609
	s_ashr_i32 s5, s11, 31
	s_lshr_b32 s5, s5, 29
	s_add_i32 s5, s11, s5
	s_ashr_i32 s6, s5, 3
	s_and_b32 s5, s5, -8
	s_ashr_i32 s4, s10, 3
	s_sub_i32 s5, s11, s5
	s_mul_i32 s4, s5, s4
	s_add_i32 s11, s4, s6
